# GEMM MFMA phases: removed the redundant s_setprio 0/1 pair between the two 16-MFMA halves and the no-op lgkmcnt wait after the barrier (MFMA phase is the critical path)
# speedup vs baseline: 1.0135x; 1.0135x over previous
; #define PG8_STAGE(bufoff, gbase, voff) do { _Pragma("unroll") for (int _i = 0; _i < 2; ++_i) \
;         __builtin_amdgcn_global_load_lds((const unsigned*)((const char*)(gbase) + (voff)[_i]), (LAS unsigned*)(lds + (bufoff) + ldsw + _i * 8192), 16, 0, 0); } while (0)
; #define PG8_LDA(dst, b, h) do { _Pragma("unroll") for (int m = 0; m < 4; ++m) _Pragma("unroll") for (int k = 0; k < 2; ++k) dst[m][k] = *(const LAS bf16x8*)(lds + PG8_SA(b, h) + aoff + m * 2048 + k * 1024); } while (0)
; #define PG8_LDB(dst, b, h) do { _Pragma("unroll") for (int n = 0; n < 2; ++n) _Pragma("unroll") for (int k = 0; k < 2; ++k) dst[n][k] = *(const LAS bf16x8*)(lds + PG8_SB(b, h) + boff + n * 2048 + k * 1024); } while (0)
; #define PG8_MMA(ai, bj, At, Bt) do { __builtin_amdgcn_s_setprio(1); _Pragma("unroll") for (int m = 0; m < 4; ++m) _Pragma("unroll") for (int n = 0; n < 2; ++n) _Pragma("unroll") for (int k = 0; k < 2; ++k) \
;         acc[ai][bj][m][n] = __builtin_amdgcn_mfma_f32_16x16x32_bf16(Bt[n][k], At[m][k], acc[ai][bj][m][n], 0, 0, 0); __builtin_amdgcn_s_setprio(0); } while (0)
; #define PG8_WAIT_V(n) asm volatile("s_waitcnt vmcnt(" #n ")" ::: "memory")
; #define PG8_WAIT_L(n) asm volatile("s_waitcnt lgkmcnt(" #n ")" ::: "memory")
; #define PG8_BAR __builtin_amdgcn_s_barrier()
; #define PG8_SCHED __builtin_amdgcn_sched_barrier(0)
; template <class Epi>
; __device__ __forceinline__ void gemm_phase(LAS unsigned char* lds, const Gemm g, const StaticOrder& S, const Epi& E) {
;     ...
;         for (int t = 0; t < nt; t += 2) {
;             const bool last = (t == nt - 2);
;             const char* a1 = cA + (size_t)(t + 1) * kstep;
;             const char* a2 = last ? nA : cA + (size_t)(t + 2) * kstep; const char* b2 = last ? nB : cB + (size_t)(t + 2) * kstep;
;             const char* a3 = a2 + kstep; const char* b3 = b2 + kstep;
;             PG8_LDB(B0, 0, 0); PG8_LDB(B1, 0, 1); PG8_SCHED; PG8_LDA(At, 0, 0); PG8_STAGE(PG8_SA(1, 1), a1 + hA, voffA);
;             PG8_WAIT_V(8); PG8_WAIT_L(0); PG8_BAR; PG8_MMA(0, 0, At, B0); PG8_MMA(0, 1, At, B1); PG8_BAR; PG8_SCHED;
;             PG8_LDA(At, 0, 1); PG8_STAGE(PG8_SB(0, 0), b2, voffB); PG8_STAGE(PG8_SB(0, 1), b2 + hB, voffB); PG8_STAGE(PG8_SA(0, 0), a2, voffA);
;             PG8_WAIT_V(8); PG8_WAIT_L(0); PG8_BAR; PG8_MMA(1, 0, At, B0); PG8_MMA(1, 1, At, B1); PG8_BAR; PG8_SCHED;
.LBB0_132:
	s_add_u32 s34, s8, 0xfffc0080
	s_addc_u32 s35, s9, -1
	s_add_i32 s42, 0, 0x10000
	s_cmp_eq_u32 s41, 12
	s_cselect_b32 s37, s7, s35
	s_cselect_b32 s36, s27, s34
	v_add_u32_e32 v153, s42, v139
	s_cselect_b32 s35, s25, s40
	s_cselect_b32 s34, s38, s39
	s_add_i32 s44, 0, 0x14000
	ds_read_b128 v[166:169], v153
	ds_read_b128 v[170:173], v153 offset:1024
	ds_read_b128 v[174:177], v153 offset:2048
	ds_read_b128 v[182:185], v153 offset:3072
	v_add_u32_e32 v153, s44, v139
	ds_read_b128 v[186:189], v153
	ds_read_b128 v[190:193], v153 offset:1024
	ds_read_b128 v[194:197], v153 offset:2048
	ds_read_b128 v[198:201], v153 offset:3072
	v_lshl_add_u64 v[178:179], s[8:9], 0, v[162:163]
	s_add_i32 m0, s19, 0xc000
	ds_read_b128 v[202:205], v149
	ds_read_b128 v[206:209], v149 offset:1024
	ds_read_b128 v[210:213], v149 offset:2048
	ds_read_b128 v[214:217], v149 offset:3072
	ds_read_b128 v[218:221], v149 offset:4096
	ds_read_b128 v[232:235], v149 offset:5120
	ds_read_b128 v[236:239], v149 offset:6144
	ds_read_b128 v[240:243], v149 offset:7168
	global_load_lds_dwordx4 v[178:179], off
	v_lshl_add_u64 v[178:179], s[8:9], 0, v[164:165]
	s_add_i32 m0, s19, 0xe000
	s_nop 0
	global_load_lds_dwordx4 v[178:179], off
	s_waitcnt vmcnt(8)
	s_waitcnt lgkmcnt(0)
	s_barrier
	s_setprio 1
	v_mfma_f32_16x16x32_bf16 v[126:129], v[166:169], v[202:205], v[126:129]
	v_mfma_f32_16x16x32_bf16 v[122:125], v[174:177], v[202:205], v[122:125]
	v_mfma_f32_16x16x32_bf16 v[110:113], v[166:169], v[210:213], v[110:113]
	v_mfma_f32_16x16x32_bf16 v[106:109], v[174:177], v[210:213], v[106:109]
	v_mfma_f32_16x16x32_bf16 v[94:97], v[166:169], v[218:221], v[94:97]
	v_mfma_f32_16x16x32_bf16 v[90:93], v[174:177], v[218:221], v[90:93]
	v_mfma_f32_16x16x32_bf16 v[78:81], v[166:169], v[236:239], v[78:81]
	v_mfma_f32_16x16x32_bf16 v[74:77], v[174:177], v[236:239], v[74:77]
	v_mfma_f32_16x16x32_bf16 v[126:129], v[170:173], v[206:209], v[126:129]
	v_mfma_f32_16x16x32_bf16 v[122:125], v[182:185], v[206:209], v[122:125]
	v_mfma_f32_16x16x32_bf16 v[110:113], v[170:173], v[214:217], v[110:113]
	v_mfma_f32_16x16x32_bf16 v[106:109], v[182:185], v[214:217], v[106:109]
	v_mfma_f32_16x16x32_bf16 v[94:97], v[170:173], v[232:235], v[94:97]
	v_mfma_f32_16x16x32_bf16 v[90:93], v[182:185], v[232:235], v[90:93]
	v_mfma_f32_16x16x32_bf16 v[78:81], v[170:173], v[240:243], v[78:81]
	v_mfma_f32_16x16x32_bf16 v[74:77], v[182:185], v[240:243], v[74:77]
	v_mfma_f32_16x16x32_bf16 v[118:121], v[186:189], v[202:205], v[118:121]
	v_mfma_f32_16x16x32_bf16 v[114:117], v[194:197], v[202:205], v[114:117]
	v_mfma_f32_16x16x32_bf16 v[102:105], v[186:189], v[210:213], v[102:105]
	v_mfma_f32_16x16x32_bf16 v[98:101], v[194:197], v[210:213], v[98:101]
	v_mfma_f32_16x16x32_bf16 v[86:89], v[186:189], v[218:221], v[86:89]
	v_mfma_f32_16x16x32_bf16 v[82:85], v[194:197], v[218:221], v[82:85]
	v_mfma_f32_16x16x32_bf16 v[70:73], v[186:189], v[236:239], v[70:73]
	v_mfma_f32_16x16x32_bf16 v[66:69], v[194:197], v[236:239], v[66:69]
	v_mfma_f32_16x16x32_bf16 v[118:121], v[190:193], v[206:209], v[118:121]
	v_mfma_f32_16x16x32_bf16 v[114:117], v[198:201], v[206:209], v[114:117]
	v_mfma_f32_16x16x32_bf16 v[102:105], v[190:193], v[214:217], v[102:105]
	v_mfma_f32_16x16x32_bf16 v[98:101], v[198:201], v[214:217], v[98:101]
	v_mfma_f32_16x16x32_bf16 v[86:89], v[190:193], v[232:235], v[86:89]
	v_mfma_f32_16x16x32_bf16 v[82:85], v[198:201], v[232:235], v[82:85]
	v_mfma_f32_16x16x32_bf16 v[70:73], v[190:193], v[240:243], v[70:73]
	v_mfma_f32_16x16x32_bf16 v[66:69], v[198:201], v[240:243], v[66:69]
	s_setprio 0
	s_barrier
	s_add_i32 s42, s42, s51
	v_lshl_add_u64 v[178:179], s[34:35], 0, v[132:133]
	s_mov_b32 m0, s42
	ds_read_b128 v[202:205], v149 offset:16384
	ds_read_b128 v[206:209], v149 offset:17408
	ds_read_b128 v[210:213], v149 offset:18432
	ds_read_b128 v[214:217], v149 offset:19456
	ds_read_b128 v[218:221], v149 offset:20480
	ds_read_b128 v[232:235], v149 offset:21504
	ds_read_b128 v[236:239], v149 offset:22528
	ds_read_b128 v[240:243], v149 offset:23552
	global_load_lds_dwordx4 v[178:179], off
	s_add_i32 m0, s42, 0x2000
	s_add_u32 s42, s34, 0x40000
	v_lshl_add_u64 v[244:245], s[34:35], 0, v[136:137]
	s_addc_u32 s43, s35, 0
	s_add_i32 s44, s44, s51
	global_load_lds_dwordx4 v[244:245], off
	v_lshl_add_u64 v[246:247], s[42:43], 0, v[132:133]
	s_mov_b32 m0, s44
	v_lshl_add_u64 v[248:249], s[36:37], 0, v[134:135]
	global_load_lds_dwordx4 v[246:247], off
	v_lshl_add_u64 v[246:247], s[42:43], 0, v[136:137]
	s_add_i32 m0, s44, 0x2000
	s_nop 0
	global_load_lds_dwordx4 v[246:247], off
	v_lshl_add_u64 v[246:247], s[36:37], 0, v[130:131]
	s_mov_b32 m0, s19
	s_nop 0
	global_load_lds_dwordx4 v[246:247], off
	s_mov_b32 m0, s56
	s_nop 0
	global_load_lds_dwordx4 v[248:249], off
	s_waitcnt vmcnt(8)
	s_waitcnt lgkmcnt(0)
	s_barrier
; #define PG8_STAGE(bufoff, gbase, voff) do { _Pragma("unroll") for (int _i = 0; _i < 2; ++_i) \
;         __builtin_amdgcn_global_load_lds((const unsigned*)((const char*)(gbase) + (voff)[_i]), (LAS unsigned*)(lds + (bufoff) + ldsw + _i * 8192), 16, 0, 0); } while (0)
; #define PG8_LDA(dst, b, h) do { _Pragma("unroll") for (int m = 0; m < 4; ++m) _Pragma("unroll") for (int k = 0; k < 2; ++k) dst[m][k] = *(const LAS bf16x8*)(lds + PG8_SA(b, h) + aoff + m * 2048 + k * 1024); } while (0)
; #define PG8_LDB(dst, b, h) do { _Pragma("unroll") for (int n = 0; n < 2; ++n) _Pragma("unroll") for (int k = 0; k < 2; ++k) dst[n][k] = *(const LAS bf16x8*)(lds + PG8_SB(b, h) + boff + n * 2048 + k * 1024); } while (0)
; #define PG8_MMA(ai, bj, At, Bt) do { __builtin_amdgcn_s_setprio(1); _Pragma("unroll") for (int m = 0; m < 4; ++m) _Pragma("unroll") for (int n = 0; n < 2; ++n) _Pragma("unroll") for (int k = 0; k < 2; ++k) \
;         acc[ai][bj][m][n] = __builtin_amdgcn_mfma_f32_16x16x32_bf16(Bt[n][k], At[m][k], acc[ai][bj][m][n], 0, 0, 0); __builtin_amdgcn_s_setprio(0); } while (0)
; #define PG8_WAIT_V(n) asm volatile("s_waitcnt vmcnt(" #n ")" ::: "memory")
; #define PG8_WAIT_L(n) asm volatile("s_waitcnt lgkmcnt(" #n ")" ::: "memory")
; #define PG8_BAR __builtin_amdgcn_s_barrier()
; #define PG8_SCHED __builtin_amdgcn_sched_barrier(0)
; template <class Epi>
; __device__ __forceinline__ void gemm_phase(LAS unsigned char* lds, const Gemm g, const StaticOrder& S, const Epi& E) {
;     ...
;             PG8_WAIT_V(8); PG8_WAIT_L(0); PG8_BAR; PG8_MMA(1, 0, At, B0); PG8_MMA(1, 1, At, B1); PG8_BAR; PG8_SCHED;
;             PG8_LDB(B0, 1, 0); PG8_LDB(B1, 1, 1); PG8_SCHED; PG8_LDA(At, 1, 0); PG8_STAGE(PG8_SA(0, 1), a2 + hA, voffA);
;             PG8_WAIT_V(8); PG8_WAIT_L(0); PG8_BAR; PG8_MMA(0, 0, At, B0); PG8_MMA(0, 1, At, B1); PG8_BAR; PG8_SCHED;
	s_setprio 1
	v_mfma_f32_16x16x32_bf16 v[62:65], v[166:169], v[202:205], v[62:65]
	v_mfma_f32_16x16x32_bf16 v[58:61], v[174:177], v[202:205], v[58:61]
	v_mfma_f32_16x16x32_bf16 v[46:49], v[166:169], v[210:213], v[46:49]
	v_mfma_f32_16x16x32_bf16 v[42:45], v[174:177], v[210:213], v[42:45]
	v_mfma_f32_16x16x32_bf16 v[30:33], v[166:169], v[218:221], v[30:33]
	v_mfma_f32_16x16x32_bf16 v[26:29], v[174:177], v[218:221], v[26:29]
	v_mfma_f32_16x16x32_bf16 v[14:17], v[166:169], v[236:239], v[14:17]
	v_mfma_f32_16x16x32_bf16 v[10:13], v[174:177], v[236:239], v[10:13]
	v_mfma_f32_16x16x32_bf16 v[62:65], v[170:173], v[206:209], v[62:65]
	v_mfma_f32_16x16x32_bf16 v[58:61], v[182:185], v[206:209], v[58:61]
	v_mfma_f32_16x16x32_bf16 v[46:49], v[170:173], v[214:217], v[46:49]
	v_mfma_f32_16x16x32_bf16 v[42:45], v[182:185], v[214:217], v[42:45]
	v_mfma_f32_16x16x32_bf16 v[30:33], v[170:173], v[232:235], v[30:33]
	v_mfma_f32_16x16x32_bf16 v[26:29], v[182:185], v[232:235], v[26:29]
	v_mfma_f32_16x16x32_bf16 v[14:17], v[170:173], v[240:243], v[14:17]
	v_mfma_f32_16x16x32_bf16 v[10:13], v[182:185], v[240:243], v[10:13]
	v_mfma_f32_16x16x32_bf16 v[54:57], v[186:189], v[202:205], v[54:57]
	v_mfma_f32_16x16x32_bf16 v[50:53], v[194:197], v[202:205], v[50:53]
	v_mfma_f32_16x16x32_bf16 v[38:41], v[186:189], v[210:213], v[38:41]
	v_mfma_f32_16x16x32_bf16 v[34:37], v[194:197], v[210:213], v[34:37]
	v_mfma_f32_16x16x32_bf16 v[22:25], v[186:189], v[218:221], v[22:25]
	v_mfma_f32_16x16x32_bf16 v[18:21], v[194:197], v[218:221], v[18:21]
	v_mfma_f32_16x16x32_bf16 v[6:9], v[186:189], v[236:239], v[6:9]
	v_mfma_f32_16x16x32_bf16 v[2:5], v[194:197], v[236:239], v[2:5]
	v_mfma_f32_16x16x32_bf16 v[54:57], v[190:193], v[206:209], v[54:57]
	v_mfma_f32_16x16x32_bf16 v[50:53], v[198:201], v[206:209], v[50:53]
	v_mfma_f32_16x16x32_bf16 v[38:41], v[190:193], v[214:217], v[38:41]
	v_mfma_f32_16x16x32_bf16 v[34:37], v[198:201], v[214:217], v[34:37]
	v_mfma_f32_16x16x32_bf16 v[22:25], v[190:193], v[232:235], v[22:25]
	v_mfma_f32_16x16x32_bf16 v[18:21], v[198:201], v[232:235], v[18:21]
	v_mfma_f32_16x16x32_bf16 v[6:9], v[190:193], v[240:243], v[6:9]
	v_mfma_f32_16x16x32_bf16 v[2:5], v[198:201], v[240:243], v[2:5]
	s_setprio 0
	s_barrier
	s_add_i32 s42, 0, 0x18000
	v_add_u32_e32 v153, s42, v139
	s_add_i32 s43, 0, 0x1c000
	ds_read_b128 v[166:169], v153
	ds_read_b128 v[170:173], v153 offset:1024
	ds_read_b128 v[174:177], v153 offset:2048
	ds_read_b128 v[182:185], v153 offset:3072
	v_add_u32_e32 v153, s43, v139
	ds_read_b128 v[186:189], v153
	ds_read_b128 v[190:193], v153 offset:1024
	ds_read_b128 v[194:197], v153 offset:2048
	ds_read_b128 v[198:201], v153 offset:3072
	s_add_u32 s36, s36, 0x40000
	s_addc_u32 s37, s37, 0
	s_mov_b32 m0, s57
	v_lshl_add_u64 v[250:251], s[36:37], 0, v[130:131]
	ds_read_b128 v[202:205], v149 offset:32768
	ds_read_b128 v[206:209], v149 offset:33792
	ds_read_b128 v[210:213], v149 offset:34816
	ds_read_b128 v[214:217], v149 offset:35840
	ds_read_b128 v[218:221], v149 offset:36864
	ds_read_b128 v[232:235], v149 offset:37888
	ds_read_b128 v[236:239], v149 offset:38912
	ds_read_b128 v[240:243], v149 offset:39936
	global_load_lds_dwordx4 v[250:251], off
	v_lshl_add_u64 v[250:251], s[36:37], 0, v[134:135]
	s_mov_b32 m0, s58
	s_nop 0
	global_load_lds_dwordx4 v[250:251], off
	s_waitcnt vmcnt(8)
	s_waitcnt lgkmcnt(0)
	s_barrier
	s_setprio 1
	v_mfma_f32_16x16x32_bf16 v[126:129], v[166:169], v[202:205], v[126:129]
	v_mfma_f32_16x16x32_bf16 v[122:125], v[174:177], v[202:205], v[122:125]
	v_mfma_f32_16x16x32_bf16 v[110:113], v[166:169], v[210:213], v[110:113]
	v_mfma_f32_16x16x32_bf16 v[106:109], v[174:177], v[210:213], v[106:109]
	v_mfma_f32_16x16x32_bf16 v[94:97], v[166:169], v[218:221], v[94:97]
	v_mfma_f32_16x16x32_bf16 v[90:93], v[174:177], v[218:221], v[90:93]
	v_mfma_f32_16x16x32_bf16 v[78:81], v[166:169], v[236:239], v[78:81]
	v_mfma_f32_16x16x32_bf16 v[74:77], v[174:177], v[236:239], v[74:77]
	v_mfma_f32_16x16x32_bf16 v[126:129], v[170:173], v[206:209], v[126:129]
	v_mfma_f32_16x16x32_bf16 v[122:125], v[182:185], v[206:209], v[122:125]
	v_mfma_f32_16x16x32_bf16 v[110:113], v[170:173], v[214:217], v[110:113]
	v_mfma_f32_16x16x32_bf16 v[106:109], v[182:185], v[214:217], v[106:109]
	v_mfma_f32_16x16x32_bf16 v[94:97], v[170:173], v[232:235], v[94:97]
	v_mfma_f32_16x16x32_bf16 v[90:93], v[182:185], v[232:235], v[90:93]
	v_mfma_f32_16x16x32_bf16 v[78:81], v[170:173], v[240:243], v[78:81]
	v_mfma_f32_16x16x32_bf16 v[74:77], v[182:185], v[240:243], v[74:77]
	v_mfma_f32_16x16x32_bf16 v[118:121], v[186:189], v[202:205], v[118:121]
	v_mfma_f32_16x16x32_bf16 v[114:117], v[194:197], v[202:205], v[114:117]
	v_mfma_f32_16x16x32_bf16 v[102:105], v[186:189], v[210:213], v[102:105]
	v_mfma_f32_16x16x32_bf16 v[98:101], v[194:197], v[210:213], v[98:101]
	v_mfma_f32_16x16x32_bf16 v[86:89], v[186:189], v[218:221], v[86:89]
	v_mfma_f32_16x16x32_bf16 v[82:85], v[194:197], v[218:221], v[82:85]
	v_mfma_f32_16x16x32_bf16 v[70:73], v[186:189], v[236:239], v[70:73]
	v_mfma_f32_16x16x32_bf16 v[66:69], v[194:197], v[236:239], v[66:69]
	v_mfma_f32_16x16x32_bf16 v[118:121], v[190:193], v[206:209], v[118:121]
	v_mfma_f32_16x16x32_bf16 v[114:117], v[198:201], v[206:209], v[114:117]
	v_mfma_f32_16x16x32_bf16 v[102:105], v[190:193], v[214:217], v[102:105]
	v_mfma_f32_16x16x32_bf16 v[98:101], v[198:201], v[214:217], v[98:101]
	v_mfma_f32_16x16x32_bf16 v[86:89], v[190:193], v[232:235], v[86:89]
	v_mfma_f32_16x16x32_bf16 v[82:85], v[198:201], v[232:235], v[82:85]
	v_mfma_f32_16x16x32_bf16 v[70:73], v[190:193], v[240:243], v[70:73]
	v_mfma_f32_16x16x32_bf16 v[66:69], v[198:201], v[240:243], v[66:69]
	s_setprio 0
	s_barrier
; #define PG8_STAGE(bufoff, gbase, voff) do { _Pragma("unroll") for (int _i = 0; _i < 2; ++_i) \
;         __builtin_amdgcn_global_load_lds((const unsigned*)((const char*)(gbase) + (voff)[_i]), (LAS unsigned*)(lds + (bufoff) + ldsw + _i * 8192), 16, 0, 0); } while (0)
; #define PG8_LDA(dst, b, h) do { _Pragma("unroll") for (int m = 0; m < 4; ++m) _Pragma("unroll") for (int k = 0; k < 2; ++k) dst[m][k] = *(const LAS bf16x8*)(lds + PG8_SA(b, h) + aoff + m * 2048 + k * 1024); } while (0)
; #define PG8_MMA(ai, bj, At, Bt) do { __builtin_amdgcn_s_setprio(1); _Pragma("unroll") for (int m = 0; m < 4; ++m) _Pragma("unroll") for (int n = 0; n < 2; ++n) _Pragma("unroll") for (int k = 0; k < 2; ++k) \
;         acc[ai][bj][m][n] = __builtin_amdgcn_mfma_f32_16x16x32_bf16(Bt[n][k], At[m][k], acc[ai][bj][m][n], 0, 0, 0); __builtin_amdgcn_s_setprio(0); } while (0)
; #define PG8_WAIT_V(n) asm volatile("s_waitcnt vmcnt(" #n ")" ::: "memory")
; #define PG8_WAIT_L(n) asm volatile("s_waitcnt lgkmcnt(" #n ")" ::: "memory")
; #define PG8_BAR __builtin_amdgcn_s_barrier()
; #define PG8_SCHED __builtin_amdgcn_sched_barrier(0)
; template <class Epi>
; __device__ __forceinline__ void gemm_phase(LAS unsigned char* lds, const Gemm g, const StaticOrder& S, const Epi& E) {
;     ...
;             PG8_LDA(At, 1, 1); PG8_STAGE(PG8_SB(1, 0), b3, voffB); PG8_STAGE(PG8_SB(1, 1), b3 + hB, voffB); PG8_STAGE(PG8_SA(1, 0), a3, voffA);
;             PG8_WAIT_V(8); PG8_WAIT_L(0); PG8_BAR; PG8_MMA(1, 0, At, B0); PG8_MMA(1, 1, At, B1); PG8_BAR; PG8_SCHED;
;         }
	s_add_i32 s36, s42, s51
	v_lshl_add_u64 v[178:179], v[178:179], 0, s[88:89]
	s_mov_b32 m0, s36
	ds_read_b128 v[202:205], v149 offset:49152
	ds_read_b128 v[206:209], v149 offset:50176
	ds_read_b128 v[210:213], v149 offset:51200
	ds_read_b128 v[214:217], v149 offset:52224
	ds_read_b128 v[218:221], v149 offset:53248
	ds_read_b128 v[232:235], v149 offset:54272
	ds_read_b128 v[236:239], v149 offset:55296
	ds_read_b128 v[240:243], v149 offset:56320
	global_load_lds_dwordx4 v[178:179], off
	s_add_i32 m0, s36, 0x2000
	s_add_u32 s34, s34, 0x40080
	v_lshl_add_u64 v[178:179], v[244:245], 0, s[88:89]
	s_addc_u32 s35, s35, 0
	s_add_i32 s36, s43, s51
	global_load_lds_dwordx4 v[178:179], off
	v_lshl_add_u64 v[178:179], s[34:35], 0, v[132:133]
	s_mov_b32 m0, s36
	s_nop 0
	global_load_lds_dwordx4 v[178:179], off
	v_lshl_add_u64 v[178:179], s[34:35], 0, v[136:137]
	s_add_i32 m0, s36, 0x2000
	s_nop 0
	global_load_lds_dwordx4 v[178:179], off
	v_lshl_add_u64 v[178:179], v[246:247], 0, s[88:89]
	s_mov_b32 m0, s60
	s_nop 0
	global_load_lds_dwordx4 v[178:179], off
	v_lshl_add_u64 v[178:179], v[248:249], 0, s[88:89]
	s_mov_b32 m0, s61
	s_nop 0
	global_load_lds_dwordx4 v[178:179], off
	s_waitcnt vmcnt(8)
	s_waitcnt lgkmcnt(0)
	s_barrier
	s_setprio 1
	v_mfma_f32_16x16x32_bf16 v[62:65], v[166:169], v[202:205], v[62:65]
	v_mfma_f32_16x16x32_bf16 v[58:61], v[174:177], v[202:205], v[58:61]
	v_mfma_f32_16x16x32_bf16 v[46:49], v[166:169], v[210:213], v[46:49]
	v_mfma_f32_16x16x32_bf16 v[42:45], v[174:177], v[210:213], v[42:45]
	v_mfma_f32_16x16x32_bf16 v[30:33], v[166:169], v[218:221], v[30:33]
	v_mfma_f32_16x16x32_bf16 v[26:29], v[174:177], v[218:221], v[26:29]
	v_mfma_f32_16x16x32_bf16 v[14:17], v[166:169], v[236:239], v[14:17]
	v_mfma_f32_16x16x32_bf16 v[10:13], v[174:177], v[236:239], v[10:13]
	v_mfma_f32_16x16x32_bf16 v[62:65], v[170:173], v[206:209], v[62:65]
	v_mfma_f32_16x16x32_bf16 v[58:61], v[182:185], v[206:209], v[58:61]
	v_mfma_f32_16x16x32_bf16 v[46:49], v[170:173], v[214:217], v[46:49]
	v_mfma_f32_16x16x32_bf16 v[42:45], v[182:185], v[214:217], v[42:45]
	v_mfma_f32_16x16x32_bf16 v[30:33], v[170:173], v[232:235], v[30:33]
	v_mfma_f32_16x16x32_bf16 v[26:29], v[182:185], v[232:235], v[26:29]
	v_mfma_f32_16x16x32_bf16 v[14:17], v[170:173], v[240:243], v[14:17]
	v_mfma_f32_16x16x32_bf16 v[10:13], v[182:185], v[240:243], v[10:13]
	v_mfma_f32_16x16x32_bf16 v[54:57], v[186:189], v[202:205], v[54:57]
	v_mfma_f32_16x16x32_bf16 v[50:53], v[194:197], v[202:205], v[50:53]
	v_mfma_f32_16x16x32_bf16 v[38:41], v[186:189], v[210:213], v[38:41]
	v_mfma_f32_16x16x32_bf16 v[34:37], v[194:197], v[210:213], v[34:37]
	v_mfma_f32_16x16x32_bf16 v[22:25], v[186:189], v[218:221], v[22:25]
	v_mfma_f32_16x16x32_bf16 v[18:21], v[194:197], v[218:221], v[18:21]
	v_mfma_f32_16x16x32_bf16 v[6:9], v[186:189], v[236:239], v[6:9]
	v_mfma_f32_16x16x32_bf16 v[2:5], v[194:197], v[236:239], v[2:5]
	v_mfma_f32_16x16x32_bf16 v[54:57], v[190:193], v[206:209], v[54:57]
	v_mfma_f32_16x16x32_bf16 v[50:53], v[198:201], v[206:209], v[50:53]
	v_mfma_f32_16x16x32_bf16 v[38:41], v[190:193], v[214:217], v[38:41]
	v_mfma_f32_16x16x32_bf16 v[34:37], v[198:201], v[214:217], v[34:37]
	v_mfma_f32_16x16x32_bf16 v[22:25], v[190:193], v[232:235], v[22:25]
	v_mfma_f32_16x16x32_bf16 v[18:21], v[198:201], v[232:235], v[18:21]
	v_mfma_f32_16x16x32_bf16 v[6:9], v[190:193], v[240:243], v[6:9]
	v_mfma_f32_16x16x32_bf16 v[2:5], v[198:201], v[240:243], v[2:5]
	s_setprio 0
	s_barrier
	s_add_i32 s41, s41, 2
	s_add_u32 s8, s8, 0x100
	s_addc_u32 s9, s9, 0
	s_add_u32 s39, s39, 0x100
	s_addc_u32 s40, s40, 0
	s_cmp_gt_u32 s41, 13
	s_cbranch_scc0 .LBB0_132
	s_and_b64 vcc, exec, s[16:17]
	s_cbranch_vccz .LBB0_135
	s_barrier

; #define PG8_STAGE(bufoff, gbase, voff) do { _Pragma("unroll") for (int _i = 0; _i < 2; ++_i) \
;         __builtin_amdgcn_global_load_lds((const unsigned*)((const char*)(gbase) + (voff)[_i]), (LAS unsigned*)(lds + (bufoff) + ldsw + _i * 8192), 16, 0, 0); } while (0)
; #define PG8_LDA(dst, b, h) do { _Pragma("unroll") for (int m = 0; m < 4; ++m) _Pragma("unroll") for (int k = 0; k < 2; ++k) dst[m][k] = *(const LAS bf16x8*)(lds + PG8_SA(b, h) + aoff + m * 2048 + k * 1024); } while (0)
; #define PG8_LDB(dst, b, h) do { _Pragma("unroll") for (int n = 0; n < 2; ++n) _Pragma("unroll") for (int k = 0; k < 2; ++k) dst[n][k] = *(const LAS bf16x8*)(lds + PG8_SB(b, h) + boff + n * 2048 + k * 1024); } while (0)
; #define PG8_MMA(ai, bj, At, Bt) do { __builtin_amdgcn_s_setprio(1); _Pragma("unroll") for (int m = 0; m < 4; ++m) _Pragma("unroll") for (int n = 0; n < 2; ++n) _Pragma("unroll") for (int k = 0; k < 2; ++k) \
;         acc[ai][bj][m][n] = __builtin_amdgcn_mfma_f32_16x16x32_bf16(Bt[n][k], At[m][k], acc[ai][bj][m][n], 0, 0, 0); __builtin_amdgcn_s_setprio(0); } while (0)
; #define PG8_WAIT_V(n) asm volatile("s_waitcnt vmcnt(" #n ")" ::: "memory")
; #define PG8_WAIT_L(n) asm volatile("s_waitcnt lgkmcnt(" #n ")" ::: "memory")
; #define PG8_BAR __builtin_amdgcn_s_barrier()
; #define PG8_SCHED __builtin_amdgcn_sched_barrier(0)
; template <class Epi>
; __device__ __forceinline__ void gemm_phase(LAS unsigned char* lds, const Gemm g, const StaticOrder& S, const Epi& E) {
;     ...
;         for (int t = 0; t < nt; t += 2) {
;             const bool last = (t == nt - 2);
;             const char* a1 = cA + (size_t)(t + 1) * kstep;
;             const char* a2 = last ? nA : cA + (size_t)(t + 2) * kstep; const char* b2 = last ? nB : cB + (size_t)(t + 2) * kstep;
;             const char* a3 = a2 + kstep; const char* b3 = b2 + kstep;
;             PG8_LDB(B0, 0, 0); PG8_LDB(B1, 0, 1); PG8_SCHED; PG8_LDA(At, 0, 0); PG8_STAGE(PG8_SA(1, 1), a1 + hA, voffA);
;             PG8_WAIT_V(8); PG8_WAIT_L(0); PG8_BAR; PG8_MMA(0, 0, At, B0); PG8_MMA(0, 1, At, B1); PG8_BAR; PG8_SCHED;
;             PG8_LDA(At, 0, 1); PG8_STAGE(PG8_SB(0, 0), b2, voffB); PG8_STAGE(PG8_SB(0, 1), b2 + hB, voffB); PG8_STAGE(PG8_SA(0, 0), a2, voffA);
;             PG8_WAIT_V(8); PG8_WAIT_L(0); PG8_BAR; PG8_MMA(1, 0, At, B0); PG8_MMA(1, 1, At, B1); PG8_BAR; PG8_SCHED;
.LBB0_518:
	s_add_u32 s30, s28, 0xfffc0080
	s_addc_u32 s31, s29, -1
	s_add_i32 s71, 0, 0x10000
	s_cmp_eq_u32 s70, 28
	s_cselect_b32 s35, s21, s31
	s_cselect_b32 s34, s27, s30
	v_add_u32_e32 v154, s71, v156
	s_cselect_b32 s31, s19, s67
	s_cselect_b32 s30, s65, s66
	s_add_i32 s73, 0, 0x14000
	ds_read_b128 v[98:101], v154
	ds_read_b128 v[102:105], v154 offset:1024
	ds_read_b128 v[158:161], v154 offset:2048
	ds_read_b128 v[162:165], v154 offset:3072
	v_add_u32_e32 v154, s73, v156
	ds_read_b128 v[166:169], v154
	ds_read_b128 v[170:173], v154 offset:1024
	ds_read_b128 v[174:177], v154 offset:2048
	ds_read_b128 v[182:185], v154 offset:3072
	v_lshl_add_u64 v[154:155], s[28:29], 0, v[150:151]
	s_add_i32 m0, s54, 0xc000
	ds_read_b128 v[186:189], v157
	ds_read_b128 v[190:193], v157 offset:1024
	ds_read_b128 v[194:197], v157 offset:2048
	ds_read_b128 v[198:201], v157 offset:3072
	ds_read_b128 v[202:205], v157 offset:4096
	ds_read_b128 v[206:209], v157 offset:5120
	ds_read_b128 v[210:213], v157 offset:6144
	ds_read_b128 v[214:217], v157 offset:7168
	global_load_lds_dwordx4 v[154:155], off
	v_lshl_add_u64 v[154:155], s[28:29], 0, v[152:153]
	s_add_i32 m0, s54, 0xe000
	s_nop 0
	global_load_lds_dwordx4 v[154:155], off
	s_waitcnt vmcnt(8)
	s_waitcnt lgkmcnt(0)
	s_barrier
	s_setprio 1
	v_mfma_f32_16x16x32_bf16 v[134:137], v[98:101], v[186:189], v[134:137]
	v_mfma_f32_16x16x32_bf16 v[130:133], v[158:161], v[186:189], v[130:133]
	v_mfma_f32_16x16x32_bf16 v[126:129], v[98:101], v[194:197], v[126:129]
	v_mfma_f32_16x16x32_bf16 v[122:125], v[158:161], v[194:197], v[122:125]
	v_mfma_f32_16x16x32_bf16 v[118:121], v[98:101], v[202:205], v[118:121]
	v_mfma_f32_16x16x32_bf16 v[114:117], v[158:161], v[202:205], v[114:117]
	v_mfma_f32_16x16x32_bf16 v[110:113], v[98:101], v[210:213], v[110:113]
	v_mfma_f32_16x16x32_bf16 v[106:109], v[158:161], v[210:213], v[106:109]
	v_mfma_f32_16x16x32_bf16 v[134:137], v[102:105], v[190:193], v[134:137]
	v_mfma_f32_16x16x32_bf16 v[130:133], v[162:165], v[190:193], v[130:133]
	v_mfma_f32_16x16x32_bf16 v[126:129], v[102:105], v[198:201], v[126:129]
	v_mfma_f32_16x16x32_bf16 v[122:125], v[162:165], v[198:201], v[122:125]
	v_mfma_f32_16x16x32_bf16 v[118:121], v[102:105], v[206:209], v[118:121]
	v_mfma_f32_16x16x32_bf16 v[114:117], v[162:165], v[206:209], v[114:117]
	v_mfma_f32_16x16x32_bf16 v[110:113], v[102:105], v[214:217], v[110:113]
	v_mfma_f32_16x16x32_bf16 v[106:109], v[162:165], v[214:217], v[106:109]
	v_mfma_f32_16x16x32_bf16 v[62:65], v[166:169], v[186:189], v[62:65]
	v_mfma_f32_16x16x32_bf16 v[58:61], v[174:177], v[186:189], v[58:61]
	v_mfma_f32_16x16x32_bf16 v[54:57], v[166:169], v[194:197], v[54:57]
	v_mfma_f32_16x16x32_bf16 v[50:53], v[174:177], v[194:197], v[50:53]
	v_mfma_f32_16x16x32_bf16 v[46:49], v[166:169], v[202:205], v[46:49]
	v_mfma_f32_16x16x32_bf16 v[42:45], v[174:177], v[202:205], v[42:45]
	v_mfma_f32_16x16x32_bf16 v[38:41], v[166:169], v[210:213], v[38:41]
	v_mfma_f32_16x16x32_bf16 v[34:37], v[174:177], v[210:213], v[34:37]
	v_mfma_f32_16x16x32_bf16 v[62:65], v[170:173], v[190:193], v[62:65]
	v_mfma_f32_16x16x32_bf16 v[58:61], v[182:185], v[190:193], v[58:61]
	v_mfma_f32_16x16x32_bf16 v[54:57], v[170:173], v[198:201], v[54:57]
	v_mfma_f32_16x16x32_bf16 v[50:53], v[182:185], v[198:201], v[50:53]
	v_mfma_f32_16x16x32_bf16 v[46:49], v[170:173], v[206:209], v[46:49]
	v_mfma_f32_16x16x32_bf16 v[42:45], v[182:185], v[206:209], v[42:45]
	v_mfma_f32_16x16x32_bf16 v[38:41], v[170:173], v[214:217], v[38:41]
	v_mfma_f32_16x16x32_bf16 v[34:37], v[182:185], v[214:217], v[34:37]
	s_setprio 0
	s_barrier
	s_add_i32 s71, s71, s53
	v_lshl_add_u64 v[154:155], s[30:31], 0, v[140:141]
	s_mov_b32 m0, s71
	ds_read_b128 v[186:189], v157 offset:16384
	ds_read_b128 v[190:193], v157 offset:17408
	ds_read_b128 v[194:197], v157 offset:18432
	ds_read_b128 v[198:201], v157 offset:19456
	ds_read_b128 v[202:205], v157 offset:20480
	ds_read_b128 v[206:209], v157 offset:21504
	ds_read_b128 v[210:213], v157 offset:22528
	ds_read_b128 v[214:217], v157 offset:23552
	global_load_lds_dwordx4 v[154:155], off
	s_add_i32 m0, s71, 0x2000
	s_add_u32 s74, s30, 0x80000
	v_lshl_add_u64 v[178:179], s[30:31], 0, v[144:145]
	s_addc_u32 s75, s31, 0
	s_add_i32 s71, s73, s53
	global_load_lds_dwordx4 v[178:179], off
	v_lshl_add_u64 v[218:219], s[74:75], 0, v[140:141]
	s_mov_b32 m0, s71
	v_lshl_add_u64 v[220:221], s[34:35], 0, v[142:143]
	global_load_lds_dwordx4 v[218:219], off
	v_lshl_add_u64 v[218:219], s[74:75], 0, v[144:145]
	s_add_i32 m0, s71, 0x2000
	s_nop 0
	global_load_lds_dwordx4 v[218:219], off
	v_lshl_add_u64 v[218:219], s[34:35], 0, v[138:139]
	s_mov_b32 m0, s54
	s_nop 0
	global_load_lds_dwordx4 v[218:219], off
	s_mov_b32 m0, s55
	s_nop 0
	global_load_lds_dwordx4 v[220:221], off
	s_waitcnt vmcnt(8)
	s_waitcnt lgkmcnt(0)
	s_barrier
; #define PG8_STAGE(bufoff, gbase, voff) do { _Pragma("unroll") for (int _i = 0; _i < 2; ++_i) \
;         __builtin_amdgcn_global_load_lds((const unsigned*)((const char*)(gbase) + (voff)[_i]), (LAS unsigned*)(lds + (bufoff) + ldsw + _i * 8192), 16, 0, 0); } while (0)
; #define PG8_LDA(dst, b, h) do { _Pragma("unroll") for (int m = 0; m < 4; ++m) _Pragma("unroll") for (int k = 0; k < 2; ++k) dst[m][k] = *(const LAS bf16x8*)(lds + PG8_SA(b, h) + aoff + m * 2048 + k * 1024); } while (0)
; #define PG8_LDB(dst, b, h) do { _Pragma("unroll") for (int n = 0; n < 2; ++n) _Pragma("unroll") for (int k = 0; k < 2; ++k) dst[n][k] = *(const LAS bf16x8*)(lds + PG8_SB(b, h) + boff + n * 2048 + k * 1024); } while (0)
; #define PG8_MMA(ai, bj, At, Bt) do { __builtin_amdgcn_s_setprio(1); _Pragma("unroll") for (int m = 0; m < 4; ++m) _Pragma("unroll") for (int n = 0; n < 2; ++n) _Pragma("unroll") for (int k = 0; k < 2; ++k) \
;         acc[ai][bj][m][n] = __builtin_amdgcn_mfma_f32_16x16x32_bf16(Bt[n][k], At[m][k], acc[ai][bj][m][n], 0, 0, 0); __builtin_amdgcn_s_setprio(0); } while (0)
; #define PG8_WAIT_V(n) asm volatile("s_waitcnt vmcnt(" #n ")" ::: "memory")
; #define PG8_WAIT_L(n) asm volatile("s_waitcnt lgkmcnt(" #n ")" ::: "memory")
; #define PG8_BAR __builtin_amdgcn_s_barrier()
; #define PG8_SCHED __builtin_amdgcn_sched_barrier(0)
; template <class Epi>
; __device__ __forceinline__ void gemm_phase(LAS unsigned char* lds, const Gemm g, const StaticOrder& S, const Epi& E) {
;     ...
;             PG8_WAIT_V(8); PG8_WAIT_L(0); PG8_BAR; PG8_MMA(1, 0, At, B0); PG8_MMA(1, 1, At, B1); PG8_BAR; PG8_SCHED;
;             PG8_LDB(B0, 1, 0); PG8_LDB(B1, 1, 1); PG8_SCHED; PG8_LDA(At, 1, 0); PG8_STAGE(PG8_SA(0, 1), a2 + hA, voffA);
;             PG8_WAIT_V(8); PG8_WAIT_L(0); PG8_BAR; PG8_MMA(0, 0, At, B0); PG8_MMA(0, 1, At, B1); PG8_BAR; PG8_SCHED;
	s_setprio 1
	v_mfma_f32_16x16x32_bf16 v[94:97], v[98:101], v[186:189], v[94:97]
	v_mfma_f32_16x16x32_bf16 v[90:93], v[158:161], v[186:189], v[90:93]
	v_mfma_f32_16x16x32_bf16 v[86:89], v[98:101], v[194:197], v[86:89]
	v_mfma_f32_16x16x32_bf16 v[82:85], v[158:161], v[194:197], v[82:85]
	v_mfma_f32_16x16x32_bf16 v[78:81], v[98:101], v[202:205], v[78:81]
	v_mfma_f32_16x16x32_bf16 v[74:77], v[158:161], v[202:205], v[74:77]
	v_mfma_f32_16x16x32_bf16 v[70:73], v[98:101], v[210:213], v[70:73]
	v_mfma_f32_16x16x32_bf16 v[66:69], v[158:161], v[210:213], v[66:69]
	v_mfma_f32_16x16x32_bf16 v[94:97], v[102:105], v[190:193], v[94:97]
	v_mfma_f32_16x16x32_bf16 v[90:93], v[162:165], v[190:193], v[90:93]
	v_mfma_f32_16x16x32_bf16 v[86:89], v[102:105], v[198:201], v[86:89]
	v_mfma_f32_16x16x32_bf16 v[82:85], v[162:165], v[198:201], v[82:85]
	v_mfma_f32_16x16x32_bf16 v[78:81], v[102:105], v[206:209], v[78:81]
	v_mfma_f32_16x16x32_bf16 v[74:77], v[162:165], v[206:209], v[74:77]
	v_mfma_f32_16x16x32_bf16 v[70:73], v[102:105], v[214:217], v[70:73]
	v_mfma_f32_16x16x32_bf16 v[66:69], v[162:165], v[214:217], v[66:69]
	v_mfma_f32_16x16x32_bf16 v[30:33], v[166:169], v[186:189], v[30:33]
	v_mfma_f32_16x16x32_bf16 v[26:29], v[174:177], v[186:189], v[26:29]
	v_mfma_f32_16x16x32_bf16 v[22:25], v[166:169], v[194:197], v[22:25]
	v_mfma_f32_16x16x32_bf16 v[18:21], v[174:177], v[194:197], v[18:21]
	v_mfma_f32_16x16x32_bf16 v[14:17], v[166:169], v[202:205], v[14:17]
	v_mfma_f32_16x16x32_bf16 v[10:13], v[174:177], v[202:205], v[10:13]
	v_mfma_f32_16x16x32_bf16 v[6:9], v[166:169], v[210:213], v[6:9]
	v_mfma_f32_16x16x32_bf16 v[2:5], v[174:177], v[210:213], v[2:5]
	v_mfma_f32_16x16x32_bf16 v[30:33], v[170:173], v[190:193], v[30:33]
	v_mfma_f32_16x16x32_bf16 v[26:29], v[182:185], v[190:193], v[26:29]
	v_mfma_f32_16x16x32_bf16 v[22:25], v[170:173], v[198:201], v[22:25]
	v_mfma_f32_16x16x32_bf16 v[18:21], v[182:185], v[198:201], v[18:21]
	v_mfma_f32_16x16x32_bf16 v[14:17], v[170:173], v[206:209], v[14:17]
	v_mfma_f32_16x16x32_bf16 v[10:13], v[182:185], v[206:209], v[10:13]
	v_mfma_f32_16x16x32_bf16 v[6:9], v[170:173], v[214:217], v[6:9]
	v_mfma_f32_16x16x32_bf16 v[2:5], v[182:185], v[214:217], v[2:5]
	s_setprio 0
	s_barrier
	s_add_i32 s71, 0, 0x18000
	s_add_i32 s73, 0, 0x1c000
	v_add_u32_e32 v162, s71, v156
	v_add_u32_e32 v180, s73, v156
	ds_read_b128 v[98:101], v162
	ds_read_b128 v[102:105], v162 offset:1024
	ds_read_b128 v[158:161], v162 offset:2048
	ds_read_b128 v[162:165], v162 offset:3072
	ds_read_b128 v[166:169], v180
	ds_read_b128 v[170:173], v180 offset:1024
	ds_read_b128 v[174:177], v180 offset:2048
	ds_read_b128 v[182:185], v180 offset:3072
	s_add_u32 s34, s34, 0x40000
	s_addc_u32 s35, s35, 0
	s_mov_b32 m0, s56
	v_lshl_add_u64 v[232:233], s[34:35], 0, v[138:139]
	ds_read_b128 v[186:189], v157 offset:32768
	ds_read_b128 v[190:193], v157 offset:33792
	ds_read_b128 v[194:197], v157 offset:34816
	ds_read_b128 v[198:201], v157 offset:35840
	ds_read_b128 v[202:205], v157 offset:36864
	ds_read_b128 v[206:209], v157 offset:37888
	ds_read_b128 v[210:213], v157 offset:38912
	ds_read_b128 v[214:217], v157 offset:39936
	global_load_lds_dwordx4 v[232:233], off
	v_lshl_add_u64 v[232:233], s[34:35], 0, v[142:143]
	s_mov_b32 m0, s57
	s_nop 0
	global_load_lds_dwordx4 v[232:233], off
	s_waitcnt vmcnt(8)
	s_waitcnt lgkmcnt(0)
	s_barrier
	s_setprio 1
	v_mfma_f32_16x16x32_bf16 v[134:137], v[98:101], v[186:189], v[134:137]
	v_mfma_f32_16x16x32_bf16 v[130:133], v[158:161], v[186:189], v[130:133]
	v_mfma_f32_16x16x32_bf16 v[126:129], v[98:101], v[194:197], v[126:129]
	v_mfma_f32_16x16x32_bf16 v[122:125], v[158:161], v[194:197], v[122:125]
	v_mfma_f32_16x16x32_bf16 v[118:121], v[98:101], v[202:205], v[118:121]
	v_mfma_f32_16x16x32_bf16 v[114:117], v[158:161], v[202:205], v[114:117]
	v_mfma_f32_16x16x32_bf16 v[110:113], v[98:101], v[210:213], v[110:113]
	v_mfma_f32_16x16x32_bf16 v[106:109], v[158:161], v[210:213], v[106:109]
	v_mfma_f32_16x16x32_bf16 v[134:137], v[102:105], v[190:193], v[134:137]
	v_mfma_f32_16x16x32_bf16 v[130:133], v[162:165], v[190:193], v[130:133]
	v_mfma_f32_16x16x32_bf16 v[126:129], v[102:105], v[198:201], v[126:129]
	v_mfma_f32_16x16x32_bf16 v[122:125], v[162:165], v[198:201], v[122:125]
	v_mfma_f32_16x16x32_bf16 v[118:121], v[102:105], v[206:209], v[118:121]
	v_mfma_f32_16x16x32_bf16 v[114:117], v[162:165], v[206:209], v[114:117]
	v_mfma_f32_16x16x32_bf16 v[110:113], v[102:105], v[214:217], v[110:113]
	v_mfma_f32_16x16x32_bf16 v[106:109], v[162:165], v[214:217], v[106:109]
	v_mfma_f32_16x16x32_bf16 v[62:65], v[166:169], v[186:189], v[62:65]
	v_mfma_f32_16x16x32_bf16 v[58:61], v[174:177], v[186:189], v[58:61]
	v_mfma_f32_16x16x32_bf16 v[54:57], v[166:169], v[194:197], v[54:57]
	v_mfma_f32_16x16x32_bf16 v[50:53], v[174:177], v[194:197], v[50:53]
	v_mfma_f32_16x16x32_bf16 v[46:49], v[166:169], v[202:205], v[46:49]
	v_mfma_f32_16x16x32_bf16 v[42:45], v[174:177], v[202:205], v[42:45]
	v_mfma_f32_16x16x32_bf16 v[38:41], v[166:169], v[210:213], v[38:41]
	v_mfma_f32_16x16x32_bf16 v[34:37], v[174:177], v[210:213], v[34:37]
	v_mfma_f32_16x16x32_bf16 v[62:65], v[170:173], v[190:193], v[62:65]
	v_mfma_f32_16x16x32_bf16 v[58:61], v[182:185], v[190:193], v[58:61]
	v_mfma_f32_16x16x32_bf16 v[54:57], v[170:173], v[198:201], v[54:57]
	v_mfma_f32_16x16x32_bf16 v[50:53], v[182:185], v[198:201], v[50:53]
	v_mfma_f32_16x16x32_bf16 v[46:49], v[170:173], v[206:209], v[46:49]
	v_mfma_f32_16x16x32_bf16 v[42:45], v[182:185], v[206:209], v[42:45]
	v_mfma_f32_16x16x32_bf16 v[38:41], v[170:173], v[214:217], v[38:41]
	v_mfma_f32_16x16x32_bf16 v[34:37], v[182:185], v[214:217], v[34:37]
	s_setprio 0
	s_barrier
; #define PG8_STAGE(bufoff, gbase, voff) do { _Pragma("unroll") for (int _i = 0; _i < 2; ++_i) \
;         __builtin_amdgcn_global_load_lds((const unsigned*)((const char*)(gbase) + (voff)[_i]), (LAS unsigned*)(lds + (bufoff) + ldsw + _i * 8192), 16, 0, 0); } while (0)
; #define PG8_LDA(dst, b, h) do { _Pragma("unroll") for (int m = 0; m < 4; ++m) _Pragma("unroll") for (int k = 0; k < 2; ++k) dst[m][k] = *(const LAS bf16x8*)(lds + PG8_SA(b, h) + aoff + m * 2048 + k * 1024); } while (0)
; #define PG8_MMA(ai, bj, At, Bt) do { __builtin_amdgcn_s_setprio(1); _Pragma("unroll") for (int m = 0; m < 4; ++m) _Pragma("unroll") for (int n = 0; n < 2; ++n) _Pragma("unroll") for (int k = 0; k < 2; ++k) \
;         acc[ai][bj][m][n] = __builtin_amdgcn_mfma_f32_16x16x32_bf16(Bt[n][k], At[m][k], acc[ai][bj][m][n], 0, 0, 0); __builtin_amdgcn_s_setprio(0); } while (0)
; #define PG8_WAIT_V(n) asm volatile("s_waitcnt vmcnt(" #n ")" ::: "memory")
; #define PG8_WAIT_L(n) asm volatile("s_waitcnt lgkmcnt(" #n ")" ::: "memory")
; #define PG8_BAR __builtin_amdgcn_s_barrier()
; #define PG8_SCHED __builtin_amdgcn_sched_barrier(0)
; template <class Epi>
; __device__ __forceinline__ void gemm_phase(LAS unsigned char* lds, const Gemm g, const StaticOrder& S, const Epi& E) {
;     ...
;             PG8_LDA(At, 1, 1); PG8_STAGE(PG8_SB(1, 0), b3, voffB); PG8_STAGE(PG8_SB(1, 1), b3 + hB, voffB); PG8_STAGE(PG8_SA(1, 0), a3, voffA);
;             PG8_WAIT_V(8); PG8_WAIT_L(0); PG8_BAR; PG8_MMA(1, 0, At, B0); PG8_MMA(1, 1, At, B1); PG8_BAR; PG8_SCHED;
;         }
	s_add_i32 s34, s71, s53
	v_lshl_add_u64 v[154:155], v[154:155], 0, s[88:89]
	s_mov_b32 m0, s34
	ds_read_b128 v[186:189], v157 offset:49152
	ds_read_b128 v[190:193], v157 offset:50176
	ds_read_b128 v[194:197], v157 offset:51200
	ds_read_b128 v[198:201], v157 offset:52224
	ds_read_b128 v[202:205], v157 offset:53248
	ds_read_b128 v[206:209], v157 offset:54272
	ds_read_b128 v[210:213], v157 offset:55296
	ds_read_b128 v[214:217], v157 offset:56320
	global_load_lds_dwordx4 v[154:155], off
	s_add_i32 m0, s34, 0x2000
	s_add_u32 s30, s30, 0x80080
	v_lshl_add_u64 v[154:155], v[178:179], 0, s[88:89]
	s_addc_u32 s31, s31, 0
	s_add_i32 s34, s73, s53
	global_load_lds_dwordx4 v[154:155], off
	v_lshl_add_u64 v[154:155], s[30:31], 0, v[140:141]
	s_mov_b32 m0, s34
	s_nop 0
	global_load_lds_dwordx4 v[154:155], off
	v_lshl_add_u64 v[154:155], s[30:31], 0, v[144:145]
	s_add_i32 m0, s34, 0x2000
	s_nop 0
	global_load_lds_dwordx4 v[154:155], off
	v_lshl_add_u64 v[154:155], v[218:219], 0, s[88:89]
	s_mov_b32 m0, s59
	s_nop 0
	global_load_lds_dwordx4 v[154:155], off
	v_lshl_add_u64 v[154:155], v[220:221], 0, s[88:89]
	s_mov_b32 m0, s60
	s_nop 0
	global_load_lds_dwordx4 v[154:155], off
	s_waitcnt vmcnt(8)
	s_waitcnt lgkmcnt(0)
	s_barrier
	s_setprio 1
	v_mfma_f32_16x16x32_bf16 v[94:97], v[98:101], v[186:189], v[94:97]
	v_mfma_f32_16x16x32_bf16 v[90:93], v[158:161], v[186:189], v[90:93]
	v_mfma_f32_16x16x32_bf16 v[86:89], v[98:101], v[194:197], v[86:89]
	v_mfma_f32_16x16x32_bf16 v[82:85], v[158:161], v[194:197], v[82:85]
	v_mfma_f32_16x16x32_bf16 v[78:81], v[98:101], v[202:205], v[78:81]
	v_mfma_f32_16x16x32_bf16 v[74:77], v[158:161], v[202:205], v[74:77]
	v_mfma_f32_16x16x32_bf16 v[70:73], v[98:101], v[210:213], v[70:73]
	v_mfma_f32_16x16x32_bf16 v[66:69], v[158:161], v[210:213], v[66:69]
	v_mfma_f32_16x16x32_bf16 v[94:97], v[102:105], v[190:193], v[94:97]
	v_mfma_f32_16x16x32_bf16 v[90:93], v[162:165], v[190:193], v[90:93]
	v_mfma_f32_16x16x32_bf16 v[86:89], v[102:105], v[198:201], v[86:89]
	v_mfma_f32_16x16x32_bf16 v[82:85], v[162:165], v[198:201], v[82:85]
	v_mfma_f32_16x16x32_bf16 v[78:81], v[102:105], v[206:209], v[78:81]
	v_mfma_f32_16x16x32_bf16 v[74:77], v[162:165], v[206:209], v[74:77]
	v_mfma_f32_16x16x32_bf16 v[70:73], v[102:105], v[214:217], v[70:73]
	v_mfma_f32_16x16x32_bf16 v[66:69], v[162:165], v[214:217], v[66:69]
	v_mfma_f32_16x16x32_bf16 v[30:33], v[166:169], v[186:189], v[30:33]
	v_mfma_f32_16x16x32_bf16 v[26:29], v[174:177], v[186:189], v[26:29]
	v_mfma_f32_16x16x32_bf16 v[22:25], v[166:169], v[194:197], v[22:25]
	v_mfma_f32_16x16x32_bf16 v[18:21], v[174:177], v[194:197], v[18:21]
	v_mfma_f32_16x16x32_bf16 v[14:17], v[166:169], v[202:205], v[14:17]
	v_mfma_f32_16x16x32_bf16 v[10:13], v[174:177], v[202:205], v[10:13]
	v_mfma_f32_16x16x32_bf16 v[6:9], v[166:169], v[210:213], v[6:9]
	v_mfma_f32_16x16x32_bf16 v[2:5], v[174:177], v[210:213], v[2:5]
	v_mfma_f32_16x16x32_bf16 v[30:33], v[170:173], v[190:193], v[30:33]
	v_mfma_f32_16x16x32_bf16 v[26:29], v[182:185], v[190:193], v[26:29]
	v_mfma_f32_16x16x32_bf16 v[22:25], v[170:173], v[198:201], v[22:25]
	v_mfma_f32_16x16x32_bf16 v[18:21], v[182:185], v[198:201], v[18:21]
	v_mfma_f32_16x16x32_bf16 v[14:17], v[170:173], v[206:209], v[14:17]
	v_mfma_f32_16x16x32_bf16 v[10:13], v[182:185], v[206:209], v[10:13]
	v_mfma_f32_16x16x32_bf16 v[6:9], v[170:173], v[214:217], v[6:9]
	v_mfma_f32_16x16x32_bf16 v[2:5], v[182:185], v[214:217], v[2:5]
	s_setprio 0
	s_barrier
	s_add_i32 s70, s70, 2
	s_add_u32 s28, s28, 0x100
	s_addc_u32 s29, s29, 0
	s_add_u32 s66, s66, 0x100
	s_addc_u32 s67, s67, 0
	s_cmp_gt_u32 s70, 29
	s_cbranch_scc0 .LBB0_518
	s_and_b64 vcc, exec, s[16:17]
	s_cbranch_vccz .LBB0_521
	s_barrier

; #define PG8_STAGE(bufoff, gbase, voff) do { _Pragma("unroll") for (int _i = 0; _i < 2; ++_i) \
;         __builtin_amdgcn_global_load_lds((const unsigned*)((const char*)(gbase) + (voff)[_i]), (LAS unsigned*)(lds + (bufoff) + ldsw + _i * 8192), 16, 0, 0); } while (0)
; #define PG8_LDA(dst, b, h) do { _Pragma("unroll") for (int m = 0; m < 4; ++m) _Pragma("unroll") for (int k = 0; k < 2; ++k) dst[m][k] = *(const LAS bf16x8*)(lds + PG8_SA(b, h) + aoff + m * 2048 + k * 1024); } while (0)
; #define PG8_LDB(dst, b, h) do { _Pragma("unroll") for (int n = 0; n < 2; ++n) _Pragma("unroll") for (int k = 0; k < 2; ++k) dst[n][k] = *(const LAS bf16x8*)(lds + PG8_SB(b, h) + boff + n * 2048 + k * 1024); } while (0)
; #define PG8_MMA(ai, bj, At, Bt) do { __builtin_amdgcn_s_setprio(1); _Pragma("unroll") for (int m = 0; m < 4; ++m) _Pragma("unroll") for (int n = 0; n < 2; ++n) _Pragma("unroll") for (int k = 0; k < 2; ++k) \
;         acc[ai][bj][m][n] = __builtin_amdgcn_mfma_f32_16x16x32_bf16(Bt[n][k], At[m][k], acc[ai][bj][m][n], 0, 0, 0); __builtin_amdgcn_s_setprio(0); } while (0)
; #define PG8_WAIT_V(n) asm volatile("s_waitcnt vmcnt(" #n ")" ::: "memory")
; #define PG8_WAIT_L(n) asm volatile("s_waitcnt lgkmcnt(" #n ")" ::: "memory")
; #define PG8_BAR __builtin_amdgcn_s_barrier()
; #define PG8_SCHED __builtin_amdgcn_sched_barrier(0)
; template <class Epi>
; __device__ __forceinline__ void gemm_phase(LAS unsigned char* lds, const Gemm g, const StaticOrder& S, const Epi& E) {
;     ...
;         for (int t = 0; t < nt; t += 2) {
;             const bool last = (t == nt - 2);
;             const char* a1 = cA + (size_t)(t + 1) * kstep;
;             const char* a2 = last ? nA : cA + (size_t)(t + 2) * kstep; const char* b2 = last ? nB : cB + (size_t)(t + 2) * kstep;
;             const char* a3 = a2 + kstep; const char* b3 = b2 + kstep;
;             PG8_LDB(B0, 0, 0); PG8_LDB(B1, 0, 1); PG8_SCHED; PG8_LDA(At, 0, 0); PG8_STAGE(PG8_SA(1, 1), a1 + hA, voffA);
;             PG8_WAIT_V(8); PG8_WAIT_L(0); PG8_BAR; PG8_MMA(0, 0, At, B0); PG8_MMA(0, 1, At, B1); PG8_BAR; PG8_SCHED;
;             PG8_LDA(At, 0, 1); PG8_STAGE(PG8_SB(0, 0), b2, voffB); PG8_STAGE(PG8_SB(0, 1), b2 + hB, voffB); PG8_STAGE(PG8_SA(0, 0), a2, voffA);
;             PG8_WAIT_V(8); PG8_WAIT_L(0); PG8_BAR; PG8_MMA(1, 0, At, B0); PG8_MMA(1, 1, At, B1); PG8_BAR; PG8_SCHED;
.LBB0_1398:
	s_add_u32 s10, s8, 0xfffc0080
	s_addc_u32 s11, s9, -1
	s_add_i32 s35, 0, 0x10000
	s_cmp_eq_u32 s31, 12
	s_cselect_b32 s41, s37, s11
	s_cselect_b32 s40, s36, s10
	s_cselect_b32 s11, s39, s29
	s_cselect_b32 s10, s38, s27
	s_add_i32 s64, 0, 0x14000
	v_add_u32_e32 v158, s35, v180
	v_add_u32_e32 v174, s64, v180
	ds_read_b128 v[146:149], v158
	ds_read_b128 v[150:153], v158 offset:1024
	ds_read_b128 v[154:157], v158 offset:2048
	ds_read_b128 v[158:161], v158 offset:3072
	ds_read_b128 v[162:165], v174
	ds_read_b128 v[166:169], v174 offset:1024
	ds_read_b128 v[170:173], v174 offset:2048
	ds_read_b128 v[174:177], v174 offset:3072
	v_lshl_add_u64 v[178:179], s[8:9], 0, v[142:143]
	s_add_i32 m0, s51, 0xc000
	ds_read_b128 v[182:185], v211
	ds_read_b128 v[186:189], v211 offset:1024
	ds_read_b128 v[190:193], v211 offset:2048
	ds_read_b128 v[194:197], v211 offset:3072
	ds_read_b128 v[198:201], v211 offset:4096
	ds_read_b128 v[202:205], v211 offset:5120
	ds_read_b128 v[216:219], v211 offset:6144
	ds_read_b128 v[232:235], v211 offset:7168
	global_load_lds_dwordx4 v[178:179], off
	v_lshl_add_u64 v[178:179], s[8:9], 0, v[144:145]
	s_add_i32 m0, s51, 0xe000
	s_nop 0
	global_load_lds_dwordx4 v[178:179], off
	s_waitcnt vmcnt(8)
	s_waitcnt lgkmcnt(0)
	s_barrier
	s_setprio 1
	v_mfma_f32_16x16x32_bf16 v[126:129], v[146:149], v[182:185], v[126:129]
	v_mfma_f32_16x16x32_bf16 v[122:125], v[154:157], v[182:185], v[122:125]
	v_mfma_f32_16x16x32_bf16 v[110:113], v[146:149], v[190:193], v[110:113]
	v_mfma_f32_16x16x32_bf16 v[106:109], v[154:157], v[190:193], v[106:109]
	v_mfma_f32_16x16x32_bf16 v[94:97], v[146:149], v[198:201], v[94:97]
	v_mfma_f32_16x16x32_bf16 v[90:93], v[154:157], v[198:201], v[90:93]
	v_mfma_f32_16x16x32_bf16 v[78:81], v[146:149], v[216:219], v[78:81]
	v_mfma_f32_16x16x32_bf16 v[74:77], v[154:157], v[216:219], v[74:77]
	v_mfma_f32_16x16x32_bf16 v[126:129], v[150:153], v[186:189], v[126:129]
	v_mfma_f32_16x16x32_bf16 v[122:125], v[158:161], v[186:189], v[122:125]
	v_mfma_f32_16x16x32_bf16 v[110:113], v[150:153], v[194:197], v[110:113]
	v_mfma_f32_16x16x32_bf16 v[106:109], v[158:161], v[194:197], v[106:109]
	v_mfma_f32_16x16x32_bf16 v[94:97], v[150:153], v[202:205], v[94:97]
	v_mfma_f32_16x16x32_bf16 v[90:93], v[158:161], v[202:205], v[90:93]
	v_mfma_f32_16x16x32_bf16 v[78:81], v[150:153], v[232:235], v[78:81]
	v_mfma_f32_16x16x32_bf16 v[74:77], v[158:161], v[232:235], v[74:77]
	v_mfma_f32_16x16x32_bf16 v[118:121], v[162:165], v[182:185], v[118:121]
	v_mfma_f32_16x16x32_bf16 v[114:117], v[170:173], v[182:185], v[114:117]
	v_mfma_f32_16x16x32_bf16 v[102:105], v[162:165], v[190:193], v[102:105]
	v_mfma_f32_16x16x32_bf16 v[98:101], v[170:173], v[190:193], v[98:101]
	v_mfma_f32_16x16x32_bf16 v[86:89], v[162:165], v[198:201], v[86:89]
	v_mfma_f32_16x16x32_bf16 v[82:85], v[170:173], v[198:201], v[82:85]
	v_mfma_f32_16x16x32_bf16 v[70:73], v[162:165], v[216:219], v[70:73]
	v_mfma_f32_16x16x32_bf16 v[66:69], v[170:173], v[216:219], v[66:69]
	v_mfma_f32_16x16x32_bf16 v[118:121], v[166:169], v[186:189], v[118:121]
	v_mfma_f32_16x16x32_bf16 v[114:117], v[174:177], v[186:189], v[114:117]
	v_mfma_f32_16x16x32_bf16 v[102:105], v[166:169], v[194:197], v[102:105]
	v_mfma_f32_16x16x32_bf16 v[98:101], v[174:177], v[194:197], v[98:101]
	v_mfma_f32_16x16x32_bf16 v[86:89], v[166:169], v[202:205], v[86:89]
	v_mfma_f32_16x16x32_bf16 v[82:85], v[174:177], v[202:205], v[82:85]
	v_mfma_f32_16x16x32_bf16 v[70:73], v[166:169], v[232:235], v[70:73]
	v_mfma_f32_16x16x32_bf16 v[66:69], v[174:177], v[232:235], v[66:69]
	s_setprio 0
	s_barrier
	s_add_i32 s35, s35, s50
	v_lshl_add_u64 v[178:179], s[10:11], 0, v[132:133]
	s_mov_b32 m0, s35
	ds_read_b128 v[182:185], v211 offset:16384
	ds_read_b128 v[186:189], v211 offset:17408
	ds_read_b128 v[190:193], v211 offset:18432
	ds_read_b128 v[194:197], v211 offset:19456
	ds_read_b128 v[198:201], v211 offset:20480
	ds_read_b128 v[202:205], v211 offset:21504
	ds_read_b128 v[216:219], v211 offset:22528
	ds_read_b128 v[232:235], v211 offset:23552
	global_load_lds_dwordx4 v[178:179], off
	s_add_i32 m0, s35, 0x2000
	s_add_u32 s42, s10, 0x40000
	v_lshl_add_u64 v[206:207], s[10:11], 0, v[136:137]
	s_addc_u32 s43, s11, 0
	s_add_i32 s35, s64, s50
	global_load_lds_dwordx4 v[206:207], off
	v_lshl_add_u64 v[220:221], s[42:43], 0, v[132:133]
	s_mov_b32 m0, s35
	v_lshl_add_u64 v[236:237], s[40:41], 0, v[134:135]
	global_load_lds_dwordx4 v[220:221], off
	v_lshl_add_u64 v[220:221], s[42:43], 0, v[136:137]
	s_add_i32 m0, s35, 0x2000
	s_nop 0
	global_load_lds_dwordx4 v[220:221], off
	v_lshl_add_u64 v[220:221], s[40:41], 0, v[130:131]
	s_mov_b32 m0, s51
	s_nop 0
	global_load_lds_dwordx4 v[220:221], off
	s_mov_b32 m0, s52
	s_nop 0
	global_load_lds_dwordx4 v[236:237], off
	s_waitcnt vmcnt(8)
	s_waitcnt lgkmcnt(0)
	s_barrier
; #define PG8_STAGE(bufoff, gbase, voff) do { _Pragma("unroll") for (int _i = 0; _i < 2; ++_i) \
;         __builtin_amdgcn_global_load_lds((const unsigned*)((const char*)(gbase) + (voff)[_i]), (LAS unsigned*)(lds + (bufoff) + ldsw + _i * 8192), 16, 0, 0); } while (0)
; #define PG8_LDA(dst, b, h) do { _Pragma("unroll") for (int m = 0; m < 4; ++m) _Pragma("unroll") for (int k = 0; k < 2; ++k) dst[m][k] = *(const LAS bf16x8*)(lds + PG8_SA(b, h) + aoff + m * 2048 + k * 1024); } while (0)
; #define PG8_LDB(dst, b, h) do { _Pragma("unroll") for (int n = 0; n < 2; ++n) _Pragma("unroll") for (int k = 0; k < 2; ++k) dst[n][k] = *(const LAS bf16x8*)(lds + PG8_SB(b, h) + boff + n * 2048 + k * 1024); } while (0)
; #define PG8_MMA(ai, bj, At, Bt) do { __builtin_amdgcn_s_setprio(1); _Pragma("unroll") for (int m = 0; m < 4; ++m) _Pragma("unroll") for (int n = 0; n < 2; ++n) _Pragma("unroll") for (int k = 0; k < 2; ++k) \
;         acc[ai][bj][m][n] = __builtin_amdgcn_mfma_f32_16x16x32_bf16(Bt[n][k], At[m][k], acc[ai][bj][m][n], 0, 0, 0); __builtin_amdgcn_s_setprio(0); } while (0)
; #define PG8_WAIT_V(n) asm volatile("s_waitcnt vmcnt(" #n ")" ::: "memory")
; #define PG8_WAIT_L(n) asm volatile("s_waitcnt lgkmcnt(" #n ")" ::: "memory")
; #define PG8_BAR __builtin_amdgcn_s_barrier()
; #define PG8_SCHED __builtin_amdgcn_sched_barrier(0)
; template <class Epi>
; __device__ __forceinline__ void gemm_phase(LAS unsigned char* lds, const Gemm g, const StaticOrder& S, const Epi& E) {
;     ...
;             PG8_WAIT_V(8); PG8_WAIT_L(0); PG8_BAR; PG8_MMA(1, 0, At, B0); PG8_MMA(1, 1, At, B1); PG8_BAR; PG8_SCHED;
;             PG8_LDB(B0, 1, 0); PG8_LDB(B1, 1, 1); PG8_SCHED; PG8_LDA(At, 1, 0); PG8_STAGE(PG8_SA(0, 1), a2 + hA, voffA);
;             PG8_WAIT_V(8); PG8_WAIT_L(0); PG8_BAR; PG8_MMA(0, 0, At, B0); PG8_MMA(0, 1, At, B1); PG8_BAR; PG8_SCHED;
	s_setprio 1
	v_mfma_f32_16x16x32_bf16 v[62:65], v[146:149], v[182:185], v[62:65]
	v_mfma_f32_16x16x32_bf16 v[58:61], v[154:157], v[182:185], v[58:61]
	v_mfma_f32_16x16x32_bf16 v[46:49], v[146:149], v[190:193], v[46:49]
	v_mfma_f32_16x16x32_bf16 v[42:45], v[154:157], v[190:193], v[42:45]
	v_mfma_f32_16x16x32_bf16 v[30:33], v[146:149], v[198:201], v[30:33]
	v_mfma_f32_16x16x32_bf16 v[26:29], v[154:157], v[198:201], v[26:29]
	v_mfma_f32_16x16x32_bf16 v[14:17], v[146:149], v[216:219], v[14:17]
	v_mfma_f32_16x16x32_bf16 v[10:13], v[154:157], v[216:219], v[10:13]
	v_mfma_f32_16x16x32_bf16 v[62:65], v[150:153], v[186:189], v[62:65]
	v_mfma_f32_16x16x32_bf16 v[58:61], v[158:161], v[186:189], v[58:61]
	v_mfma_f32_16x16x32_bf16 v[46:49], v[150:153], v[194:197], v[46:49]
	v_mfma_f32_16x16x32_bf16 v[42:45], v[158:161], v[194:197], v[42:45]
	v_mfma_f32_16x16x32_bf16 v[30:33], v[150:153], v[202:205], v[30:33]
	v_mfma_f32_16x16x32_bf16 v[26:29], v[158:161], v[202:205], v[26:29]
	v_mfma_f32_16x16x32_bf16 v[14:17], v[150:153], v[232:235], v[14:17]
	v_mfma_f32_16x16x32_bf16 v[10:13], v[158:161], v[232:235], v[10:13]
	v_mfma_f32_16x16x32_bf16 v[54:57], v[162:165], v[182:185], v[54:57]
	v_mfma_f32_16x16x32_bf16 v[50:53], v[170:173], v[182:185], v[50:53]
	v_mfma_f32_16x16x32_bf16 v[38:41], v[162:165], v[190:193], v[38:41]
	v_mfma_f32_16x16x32_bf16 v[34:37], v[170:173], v[190:193], v[34:37]
	v_mfma_f32_16x16x32_bf16 v[22:25], v[162:165], v[198:201], v[22:25]
	v_mfma_f32_16x16x32_bf16 v[18:21], v[170:173], v[198:201], v[18:21]
	v_mfma_f32_16x16x32_bf16 v[6:9], v[162:165], v[216:219], v[6:9]
	v_mfma_f32_16x16x32_bf16 v[2:5], v[170:173], v[216:219], v[2:5]
	v_mfma_f32_16x16x32_bf16 v[54:57], v[166:169], v[186:189], v[54:57]
	v_mfma_f32_16x16x32_bf16 v[50:53], v[174:177], v[186:189], v[50:53]
	v_mfma_f32_16x16x32_bf16 v[38:41], v[166:169], v[194:197], v[38:41]
	v_mfma_f32_16x16x32_bf16 v[34:37], v[174:177], v[194:197], v[34:37]
	v_mfma_f32_16x16x32_bf16 v[22:25], v[166:169], v[202:205], v[22:25]
	v_mfma_f32_16x16x32_bf16 v[18:21], v[174:177], v[202:205], v[18:21]
	v_mfma_f32_16x16x32_bf16 v[6:9], v[166:169], v[232:235], v[6:9]
	v_mfma_f32_16x16x32_bf16 v[2:5], v[174:177], v[232:235], v[2:5]
	s_setprio 0
	s_barrier
	s_add_i32 s35, 0, 0x18000
	s_add_i32 s42, 0, 0x1c000
	v_add_u32_e32 v158, s35, v180
	v_add_u32_e32 v174, s42, v180
	ds_read_b128 v[146:149], v158
	ds_read_b128 v[150:153], v158 offset:1024
	ds_read_b128 v[154:157], v158 offset:2048
	ds_read_b128 v[158:161], v158 offset:3072
	ds_read_b128 v[162:165], v174
	ds_read_b128 v[166:169], v174 offset:1024
	ds_read_b128 v[170:173], v174 offset:2048
	ds_read_b128 v[174:177], v174 offset:3072
	s_add_u32 s40, s40, 0x40000
	s_addc_u32 s41, s41, 0
	s_mov_b32 m0, s53
	v_lshl_add_u64 v[238:239], s[40:41], 0, v[130:131]
	ds_read_b128 v[182:185], v211 offset:32768
	ds_read_b128 v[186:189], v211 offset:33792
	ds_read_b128 v[190:193], v211 offset:34816
	ds_read_b128 v[194:197], v211 offset:35840
	ds_read_b128 v[198:201], v211 offset:36864
	ds_read_b128 v[202:205], v211 offset:37888
	ds_read_b128 v[216:219], v211 offset:38912
	ds_read_b128 v[232:235], v211 offset:39936
	global_load_lds_dwordx4 v[238:239], off
	v_lshl_add_u64 v[238:239], s[40:41], 0, v[134:135]
	s_mov_b32 m0, s54
	s_nop 0
	global_load_lds_dwordx4 v[238:239], off
	s_waitcnt vmcnt(8)
	s_waitcnt lgkmcnt(0)
	s_barrier
	s_setprio 1
	v_mfma_f32_16x16x32_bf16 v[126:129], v[146:149], v[182:185], v[126:129]
	v_mfma_f32_16x16x32_bf16 v[122:125], v[154:157], v[182:185], v[122:125]
	v_mfma_f32_16x16x32_bf16 v[110:113], v[146:149], v[190:193], v[110:113]
	v_mfma_f32_16x16x32_bf16 v[106:109], v[154:157], v[190:193], v[106:109]
	v_mfma_f32_16x16x32_bf16 v[94:97], v[146:149], v[198:201], v[94:97]
	v_mfma_f32_16x16x32_bf16 v[90:93], v[154:157], v[198:201], v[90:93]
	v_mfma_f32_16x16x32_bf16 v[78:81], v[146:149], v[216:219], v[78:81]
	v_mfma_f32_16x16x32_bf16 v[74:77], v[154:157], v[216:219], v[74:77]
	v_mfma_f32_16x16x32_bf16 v[126:129], v[150:153], v[186:189], v[126:129]
	v_mfma_f32_16x16x32_bf16 v[122:125], v[158:161], v[186:189], v[122:125]
	v_mfma_f32_16x16x32_bf16 v[110:113], v[150:153], v[194:197], v[110:113]
	v_mfma_f32_16x16x32_bf16 v[106:109], v[158:161], v[194:197], v[106:109]
	v_mfma_f32_16x16x32_bf16 v[94:97], v[150:153], v[202:205], v[94:97]
	v_mfma_f32_16x16x32_bf16 v[90:93], v[158:161], v[202:205], v[90:93]
	v_mfma_f32_16x16x32_bf16 v[78:81], v[150:153], v[232:235], v[78:81]
	v_mfma_f32_16x16x32_bf16 v[74:77], v[158:161], v[232:235], v[74:77]
	v_mfma_f32_16x16x32_bf16 v[118:121], v[162:165], v[182:185], v[118:121]
	v_mfma_f32_16x16x32_bf16 v[114:117], v[170:173], v[182:185], v[114:117]
	v_mfma_f32_16x16x32_bf16 v[102:105], v[162:165], v[190:193], v[102:105]
	v_mfma_f32_16x16x32_bf16 v[98:101], v[170:173], v[190:193], v[98:101]
	v_mfma_f32_16x16x32_bf16 v[86:89], v[162:165], v[198:201], v[86:89]
	v_mfma_f32_16x16x32_bf16 v[82:85], v[170:173], v[198:201], v[82:85]
	v_mfma_f32_16x16x32_bf16 v[70:73], v[162:165], v[216:219], v[70:73]
	v_mfma_f32_16x16x32_bf16 v[66:69], v[170:173], v[216:219], v[66:69]
	v_mfma_f32_16x16x32_bf16 v[118:121], v[166:169], v[186:189], v[118:121]
	v_mfma_f32_16x16x32_bf16 v[114:117], v[174:177], v[186:189], v[114:117]
	v_mfma_f32_16x16x32_bf16 v[102:105], v[166:169], v[194:197], v[102:105]
	v_mfma_f32_16x16x32_bf16 v[98:101], v[174:177], v[194:197], v[98:101]
	v_mfma_f32_16x16x32_bf16 v[86:89], v[166:169], v[202:205], v[86:89]
	v_mfma_f32_16x16x32_bf16 v[82:85], v[174:177], v[202:205], v[82:85]
	v_mfma_f32_16x16x32_bf16 v[70:73], v[166:169], v[232:235], v[70:73]
	v_mfma_f32_16x16x32_bf16 v[66:69], v[174:177], v[232:235], v[66:69]
	s_setprio 0
	s_barrier
; #define PG8_STAGE(bufoff, gbase, voff) do { _Pragma("unroll") for (int _i = 0; _i < 2; ++_i) \
;         __builtin_amdgcn_global_load_lds((const unsigned*)((const char*)(gbase) + (voff)[_i]), (LAS unsigned*)(lds + (bufoff) + ldsw + _i * 8192), 16, 0, 0); } while (0)
; #define PG8_LDA(dst, b, h) do { _Pragma("unroll") for (int m = 0; m < 4; ++m) _Pragma("unroll") for (int k = 0; k < 2; ++k) dst[m][k] = *(const LAS bf16x8*)(lds + PG8_SA(b, h) + aoff + m * 2048 + k * 1024); } while (0)
; #define PG8_MMA(ai, bj, At, Bt) do { __builtin_amdgcn_s_setprio(1); _Pragma("unroll") for (int m = 0; m < 4; ++m) _Pragma("unroll") for (int n = 0; n < 2; ++n) _Pragma("unroll") for (int k = 0; k < 2; ++k) \
;         acc[ai][bj][m][n] = __builtin_amdgcn_mfma_f32_16x16x32_bf16(Bt[n][k], At[m][k], acc[ai][bj][m][n], 0, 0, 0); __builtin_amdgcn_s_setprio(0); } while (0)
; #define PG8_WAIT_V(n) asm volatile("s_waitcnt vmcnt(" #n ")" ::: "memory")
; #define PG8_WAIT_L(n) asm volatile("s_waitcnt lgkmcnt(" #n ")" ::: "memory")
; #define PG8_BAR __builtin_amdgcn_s_barrier()
; #define PG8_SCHED __builtin_amdgcn_sched_barrier(0)
; template <class Epi>
; __device__ __forceinline__ void gemm_phase(LAS unsigned char* lds, const Gemm g, const StaticOrder& S, const Epi& E) {
;     ...
;             PG8_LDA(At, 1, 1); PG8_STAGE(PG8_SB(1, 0), b3, voffB); PG8_STAGE(PG8_SB(1, 1), b3 + hB, voffB); PG8_STAGE(PG8_SA(1, 0), a3, voffA);
;             PG8_WAIT_V(8); PG8_WAIT_L(0); PG8_BAR; PG8_MMA(1, 0, At, B0); PG8_MMA(1, 1, At, B1); PG8_BAR; PG8_SCHED;
;         }
	s_add_i32 s35, s35, s50
	v_lshl_add_u64 v[178:179], v[178:179], 0, s[88:89]
	s_mov_b32 m0, s35
	ds_read_b128 v[182:185], v211 offset:49152
	ds_read_b128 v[186:189], v211 offset:50176
	ds_read_b128 v[190:193], v211 offset:51200
	ds_read_b128 v[194:197], v211 offset:52224
	ds_read_b128 v[198:201], v211 offset:53248
	ds_read_b128 v[202:205], v211 offset:54272
	ds_read_b128 v[216:219], v211 offset:55296
	ds_read_b128 v[232:235], v211 offset:56320
	global_load_lds_dwordx4 v[178:179], off
	s_add_i32 m0, s35, 0x2000
	s_add_u32 s10, s10, 0x40080
	v_lshl_add_u64 v[178:179], v[206:207], 0, s[88:89]
	s_addc_u32 s11, s11, 0
	s_add_i32 s35, s42, s50
	global_load_lds_dwordx4 v[178:179], off
	v_lshl_add_u64 v[178:179], s[10:11], 0, v[132:133]
	s_mov_b32 m0, s35
	s_nop 0
	global_load_lds_dwordx4 v[178:179], off
	v_lshl_add_u64 v[178:179], s[10:11], 0, v[136:137]
	s_add_i32 m0, s35, 0x2000
	s_nop 0
	global_load_lds_dwordx4 v[178:179], off
	v_lshl_add_u64 v[178:179], v[220:221], 0, s[88:89]
	s_mov_b32 m0, s55
	s_nop 0
	global_load_lds_dwordx4 v[178:179], off
	v_lshl_add_u64 v[178:179], v[236:237], 0, s[88:89]
	s_mov_b32 m0, s56
	s_nop 0
	global_load_lds_dwordx4 v[178:179], off
	s_waitcnt vmcnt(8)
	s_waitcnt lgkmcnt(0)
	s_barrier
	s_setprio 1
	v_mfma_f32_16x16x32_bf16 v[62:65], v[146:149], v[182:185], v[62:65]
	v_mfma_f32_16x16x32_bf16 v[58:61], v[154:157], v[182:185], v[58:61]
	v_mfma_f32_16x16x32_bf16 v[46:49], v[146:149], v[190:193], v[46:49]
	v_mfma_f32_16x16x32_bf16 v[42:45], v[154:157], v[190:193], v[42:45]
	v_mfma_f32_16x16x32_bf16 v[30:33], v[146:149], v[198:201], v[30:33]
	v_mfma_f32_16x16x32_bf16 v[26:29], v[154:157], v[198:201], v[26:29]
	v_mfma_f32_16x16x32_bf16 v[14:17], v[146:149], v[216:219], v[14:17]
	v_mfma_f32_16x16x32_bf16 v[10:13], v[154:157], v[216:219], v[10:13]
	v_mfma_f32_16x16x32_bf16 v[62:65], v[150:153], v[186:189], v[62:65]
	v_mfma_f32_16x16x32_bf16 v[58:61], v[158:161], v[186:189], v[58:61]
	v_mfma_f32_16x16x32_bf16 v[46:49], v[150:153], v[194:197], v[46:49]
	v_mfma_f32_16x16x32_bf16 v[42:45], v[158:161], v[194:197], v[42:45]
	v_mfma_f32_16x16x32_bf16 v[30:33], v[150:153], v[202:205], v[30:33]
	v_mfma_f32_16x16x32_bf16 v[26:29], v[158:161], v[202:205], v[26:29]
	v_mfma_f32_16x16x32_bf16 v[14:17], v[150:153], v[232:235], v[14:17]
	v_mfma_f32_16x16x32_bf16 v[10:13], v[158:161], v[232:235], v[10:13]
	v_mfma_f32_16x16x32_bf16 v[54:57], v[162:165], v[182:185], v[54:57]
	v_mfma_f32_16x16x32_bf16 v[50:53], v[170:173], v[182:185], v[50:53]
	v_mfma_f32_16x16x32_bf16 v[38:41], v[162:165], v[190:193], v[38:41]
	v_mfma_f32_16x16x32_bf16 v[34:37], v[170:173], v[190:193], v[34:37]
	v_mfma_f32_16x16x32_bf16 v[22:25], v[162:165], v[198:201], v[22:25]
	v_mfma_f32_16x16x32_bf16 v[18:21], v[170:173], v[198:201], v[18:21]
	v_mfma_f32_16x16x32_bf16 v[6:9], v[162:165], v[216:219], v[6:9]
	v_mfma_f32_16x16x32_bf16 v[2:5], v[170:173], v[216:219], v[2:5]
	v_mfma_f32_16x16x32_bf16 v[54:57], v[166:169], v[186:189], v[54:57]
	v_mfma_f32_16x16x32_bf16 v[50:53], v[174:177], v[186:189], v[50:53]
	v_mfma_f32_16x16x32_bf16 v[38:41], v[166:169], v[194:197], v[38:41]
	v_mfma_f32_16x16x32_bf16 v[34:37], v[174:177], v[194:197], v[34:37]
	v_mfma_f32_16x16x32_bf16 v[22:25], v[166:169], v[202:205], v[22:25]
	v_mfma_f32_16x16x32_bf16 v[18:21], v[174:177], v[202:205], v[18:21]
	v_mfma_f32_16x16x32_bf16 v[6:9], v[166:169], v[232:235], v[6:9]
	v_mfma_f32_16x16x32_bf16 v[2:5], v[174:177], v[232:235], v[2:5]
	s_setprio 0
	s_barrier
	s_add_i32 s31, s31, 2
	s_add_u32 s8, s8, 0x100
	s_addc_u32 s9, s9, 0
	s_add_u32 s27, s27, 0x100
	s_addc_u32 s29, s29, 0
	s_cmp_gt_u32 s31, 13
	s_cbranch_scc0 .LBB0_1398
	s_and_b64 vcc, exec, s[16:17]
	s_cbranch_vccz .LBB0_1401
	s_barrier

; #define PG8_STAGE(bufoff, gbase, voff) do { _Pragma("unroll") for (int _i = 0; _i < 2; ++_i) \
;         __builtin_amdgcn_global_load_lds((const unsigned*)((const char*)(gbase) + (voff)[_i]), (LAS unsigned*)(lds + (bufoff) + ldsw + _i * 8192), 16, 0, 0); } while (0)
; #define PG8_LDA(dst, b, h) do { _Pragma("unroll") for (int m = 0; m < 4; ++m) _Pragma("unroll") for (int k = 0; k < 2; ++k) dst[m][k] = *(const LAS bf16x8*)(lds + PG8_SA(b, h) + aoff + m * 2048 + k * 1024); } while (0)
; #define PG8_LDB(dst, b, h) do { _Pragma("unroll") for (int n = 0; n < 2; ++n) _Pragma("unroll") for (int k = 0; k < 2; ++k) dst[n][k] = *(const LAS bf16x8*)(lds + PG8_SB(b, h) + boff + n * 2048 + k * 1024); } while (0)
; #define PG8_MMA(ai, bj, At, Bt) do { __builtin_amdgcn_s_setprio(1); _Pragma("unroll") for (int m = 0; m < 4; ++m) _Pragma("unroll") for (int n = 0; n < 2; ++n) _Pragma("unroll") for (int k = 0; k < 2; ++k) \
;         acc[ai][bj][m][n] = __builtin_amdgcn_mfma_f32_16x16x32_bf16(Bt[n][k], At[m][k], acc[ai][bj][m][n], 0, 0, 0); __builtin_amdgcn_s_setprio(0); } while (0)
; #define PG8_WAIT_V(n) asm volatile("s_waitcnt vmcnt(" #n ")" ::: "memory")
; #define PG8_WAIT_L(n) asm volatile("s_waitcnt lgkmcnt(" #n ")" ::: "memory")
; #define PG8_BAR __builtin_amdgcn_s_barrier()
; #define PG8_SCHED __builtin_amdgcn_sched_barrier(0)
; template <class Epi>
; __device__ __forceinline__ void gemm_phase(LAS unsigned char* lds, const Gemm g, const StaticOrder& S, const Epi& E) {
;     ...
;         for (int t = 0; t < nt; t += 2) {
;             const bool last = (t == nt - 2);
;             const char* a1 = cA + (size_t)(t + 1) * kstep;
;             const char* a2 = last ? nA : cA + (size_t)(t + 2) * kstep; const char* b2 = last ? nB : cB + (size_t)(t + 2) * kstep;
;             const char* a3 = a2 + kstep; const char* b3 = b2 + kstep;
;             PG8_LDB(B0, 0, 0); PG8_LDB(B1, 0, 1); PG8_SCHED; PG8_LDA(At, 0, 0); PG8_STAGE(PG8_SA(1, 1), a1 + hA, voffA);
;             PG8_WAIT_V(8); PG8_WAIT_L(0); PG8_BAR; PG8_MMA(0, 0, At, B0); PG8_MMA(0, 1, At, B1); PG8_BAR; PG8_SCHED;
;             PG8_LDA(At, 0, 1); PG8_STAGE(PG8_SB(0, 0), b2, voffB); PG8_STAGE(PG8_SB(0, 1), b2 + hB, voffB); PG8_STAGE(PG8_SA(0, 0), a2, voffA);
;             PG8_WAIT_V(8); PG8_WAIT_L(0); PG8_BAR; PG8_MMA(1, 0, At, B0); PG8_MMA(1, 1, At, B1); PG8_BAR; PG8_SCHED;
.LBB0_1550:
	s_add_u32 s22, s20, 0xfffc0080
	s_addc_u32 s23, s21, -1
	s_add_i32 s51, 0, 0x10000
	s_cmp_eq_u32 s50, 12
	s_cselect_b32 s25, s15, s23
	s_cselect_b32 s24, s46, s22
	v_add_u32_e32 v142, s51, v143
	s_cselect_b32 s23, s13, s49
	s_cselect_b32 s22, s47, s48
	s_add_i32 s54, 0, 0x14000
	ds_read_b128 v[148:151], v142
	ds_read_b128 v[152:155], v142 offset:1024
	ds_read_b128 v[156:159], v142 offset:2048
	ds_read_b128 v[160:163], v142 offset:3072
	v_add_u32_e32 v142, s54, v143
	ds_read_b128 v[164:167], v142
	ds_read_b128 v[168:171], v142 offset:1024
	ds_read_b128 v[172:175], v142 offset:2048
	ds_read_b128 v[176:179], v142 offset:3072
	v_lshl_add_u64 v[214:215], s[20:21], 0, v[138:139]
	s_add_i32 m0, s34, 0xc000
	ds_read_b128 v[182:185], v147
	ds_read_b128 v[186:189], v147 offset:1024
	ds_read_b128 v[190:193], v147 offset:2048
	ds_read_b128 v[194:197], v147 offset:3072
	ds_read_b128 v[198:201], v147 offset:4096
	ds_read_b128 v[202:205], v147 offset:5120
	ds_read_b128 v[206:209], v147 offset:6144
	ds_read_b128 v[210:213], v147 offset:7168
	global_load_lds_dwordx4 v[214:215], off
	v_lshl_add_u64 v[214:215], s[20:21], 0, v[140:141]
	s_add_i32 m0, s34, 0xe000
	s_nop 0
	global_load_lds_dwordx4 v[214:215], off
	s_waitcnt vmcnt(8)
	s_waitcnt lgkmcnt(0)
	s_barrier
	s_setprio 1
	v_mfma_f32_16x16x32_bf16 v[126:129], v[148:151], v[182:185], v[126:129]
	v_mfma_f32_16x16x32_bf16 v[122:125], v[156:159], v[182:185], v[122:125]
	v_mfma_f32_16x16x32_bf16 v[110:113], v[148:151], v[190:193], v[110:113]
	v_mfma_f32_16x16x32_bf16 v[106:109], v[156:159], v[190:193], v[106:109]
	v_mfma_f32_16x16x32_bf16 v[94:97], v[148:151], v[198:201], v[94:97]
	v_mfma_f32_16x16x32_bf16 v[90:93], v[156:159], v[198:201], v[90:93]
	v_mfma_f32_16x16x32_bf16 v[78:81], v[148:151], v[206:209], v[78:81]
	v_mfma_f32_16x16x32_bf16 v[74:77], v[156:159], v[206:209], v[74:77]
	v_mfma_f32_16x16x32_bf16 v[126:129], v[152:155], v[186:189], v[126:129]
	v_mfma_f32_16x16x32_bf16 v[122:125], v[160:163], v[186:189], v[122:125]
	v_mfma_f32_16x16x32_bf16 v[110:113], v[152:155], v[194:197], v[110:113]
	v_mfma_f32_16x16x32_bf16 v[106:109], v[160:163], v[194:197], v[106:109]
	v_mfma_f32_16x16x32_bf16 v[94:97], v[152:155], v[202:205], v[94:97]
	v_mfma_f32_16x16x32_bf16 v[90:93], v[160:163], v[202:205], v[90:93]
	v_mfma_f32_16x16x32_bf16 v[78:81], v[152:155], v[210:213], v[78:81]
	v_mfma_f32_16x16x32_bf16 v[74:77], v[160:163], v[210:213], v[74:77]
	v_mfma_f32_16x16x32_bf16 v[118:121], v[164:167], v[182:185], v[118:121]
	v_mfma_f32_16x16x32_bf16 v[114:117], v[172:175], v[182:185], v[114:117]
	v_mfma_f32_16x16x32_bf16 v[102:105], v[164:167], v[190:193], v[102:105]
	v_mfma_f32_16x16x32_bf16 v[98:101], v[172:175], v[190:193], v[98:101]
	v_mfma_f32_16x16x32_bf16 v[86:89], v[164:167], v[198:201], v[86:89]
	v_mfma_f32_16x16x32_bf16 v[82:85], v[172:175], v[198:201], v[82:85]
	v_mfma_f32_16x16x32_bf16 v[70:73], v[164:167], v[206:209], v[70:73]
	v_mfma_f32_16x16x32_bf16 v[66:69], v[172:175], v[206:209], v[66:69]
	v_mfma_f32_16x16x32_bf16 v[118:121], v[168:171], v[186:189], v[118:121]
	v_mfma_f32_16x16x32_bf16 v[114:117], v[176:179], v[186:189], v[114:117]
	v_mfma_f32_16x16x32_bf16 v[102:105], v[168:171], v[194:197], v[102:105]
	v_mfma_f32_16x16x32_bf16 v[98:101], v[176:179], v[194:197], v[98:101]
	v_mfma_f32_16x16x32_bf16 v[86:89], v[168:171], v[202:205], v[86:89]
	v_mfma_f32_16x16x32_bf16 v[82:85], v[176:179], v[202:205], v[82:85]
	v_mfma_f32_16x16x32_bf16 v[70:73], v[168:171], v[210:213], v[70:73]
	v_mfma_f32_16x16x32_bf16 v[66:69], v[176:179], v[210:213], v[66:69]
	s_setprio 0
	s_barrier
	s_add_i32 s51, s51, s31
	v_lshl_add_u64 v[214:215], s[22:23], 0, v[134:135]
	s_mov_b32 m0, s51
	ds_read_b128 v[182:185], v147 offset:16384
	ds_read_b128 v[186:189], v147 offset:17408
	ds_read_b128 v[190:193], v147 offset:18432
	ds_read_b128 v[194:197], v147 offset:19456
	ds_read_b128 v[198:201], v147 offset:20480
	ds_read_b128 v[202:205], v147 offset:21504
	ds_read_b128 v[206:209], v147 offset:22528
	ds_read_b128 v[210:213], v147 offset:23552
	global_load_lds_dwordx4 v[214:215], off
	s_add_i32 m0, s51, 0x2000
	s_add_u32 s52, s22, 0x40000
	v_lshl_add_u64 v[216:217], s[22:23], 0, v[130:131]
	s_addc_u32 s53, s23, 0
	s_add_i32 s51, s54, s31
	global_load_lds_dwordx4 v[216:217], off
	v_lshl_add_u64 v[218:219], s[52:53], 0, v[134:135]
	s_mov_b32 m0, s51
	v_lshl_add_u64 v[220:221], s[24:25], 0, v[132:133]
	global_load_lds_dwordx4 v[218:219], off
	v_lshl_add_u64 v[218:219], s[52:53], 0, v[130:131]
	s_add_i32 m0, s51, 0x2000
	s_nop 0
	global_load_lds_dwordx4 v[218:219], off
	v_lshl_add_u64 v[218:219], s[24:25], 0, v[136:137]
	s_mov_b32 m0, s34
	s_nop 0
	global_load_lds_dwordx4 v[218:219], off
	s_mov_b32 m0, s35
	s_nop 0
	global_load_lds_dwordx4 v[220:221], off
	s_waitcnt vmcnt(8)
	s_waitcnt lgkmcnt(0)
	s_barrier
; #define PG8_STAGE(bufoff, gbase, voff) do { _Pragma("unroll") for (int _i = 0; _i < 2; ++_i) \
;         __builtin_amdgcn_global_load_lds((const unsigned*)((const char*)(gbase) + (voff)[_i]), (LAS unsigned*)(lds + (bufoff) + ldsw + _i * 8192), 16, 0, 0); } while (0)
; #define PG8_LDA(dst, b, h) do { _Pragma("unroll") for (int m = 0; m < 4; ++m) _Pragma("unroll") for (int k = 0; k < 2; ++k) dst[m][k] = *(const LAS bf16x8*)(lds + PG8_SA(b, h) + aoff + m * 2048 + k * 1024); } while (0)
; #define PG8_LDB(dst, b, h) do { _Pragma("unroll") for (int n = 0; n < 2; ++n) _Pragma("unroll") for (int k = 0; k < 2; ++k) dst[n][k] = *(const LAS bf16x8*)(lds + PG8_SB(b, h) + boff + n * 2048 + k * 1024); } while (0)
; #define PG8_MMA(ai, bj, At, Bt) do { __builtin_amdgcn_s_setprio(1); _Pragma("unroll") for (int m = 0; m < 4; ++m) _Pragma("unroll") for (int n = 0; n < 2; ++n) _Pragma("unroll") for (int k = 0; k < 2; ++k) \
;         acc[ai][bj][m][n] = __builtin_amdgcn_mfma_f32_16x16x32_bf16(Bt[n][k], At[m][k], acc[ai][bj][m][n], 0, 0, 0); __builtin_amdgcn_s_setprio(0); } while (0)
; #define PG8_WAIT_V(n) asm volatile("s_waitcnt vmcnt(" #n ")" ::: "memory")
; #define PG8_WAIT_L(n) asm volatile("s_waitcnt lgkmcnt(" #n ")" ::: "memory")
; #define PG8_BAR __builtin_amdgcn_s_barrier()
; #define PG8_SCHED __builtin_amdgcn_sched_barrier(0)
; template <class Epi>
; __device__ __forceinline__ void gemm_phase(LAS unsigned char* lds, const Gemm g, const StaticOrder& S, const Epi& E) {
;     ...
;             PG8_WAIT_V(8); PG8_WAIT_L(0); PG8_BAR; PG8_MMA(1, 0, At, B0); PG8_MMA(1, 1, At, B1); PG8_BAR; PG8_SCHED;
;             PG8_LDB(B0, 1, 0); PG8_LDB(B1, 1, 1); PG8_SCHED; PG8_LDA(At, 1, 0); PG8_STAGE(PG8_SA(0, 1), a2 + hA, voffA);
;             PG8_WAIT_V(8); PG8_WAIT_L(0); PG8_BAR; PG8_MMA(0, 0, At, B0); PG8_MMA(0, 1, At, B1); PG8_BAR; PG8_SCHED;
	s_setprio 1
	v_mfma_f32_16x16x32_bf16 v[62:65], v[148:151], v[182:185], v[62:65]
	v_mfma_f32_16x16x32_bf16 v[58:61], v[156:159], v[182:185], v[58:61]
	v_mfma_f32_16x16x32_bf16 v[46:49], v[148:151], v[190:193], v[46:49]
	v_mfma_f32_16x16x32_bf16 v[42:45], v[156:159], v[190:193], v[42:45]
	v_mfma_f32_16x16x32_bf16 v[30:33], v[148:151], v[198:201], v[30:33]
	v_mfma_f32_16x16x32_bf16 v[26:29], v[156:159], v[198:201], v[26:29]
	v_mfma_f32_16x16x32_bf16 v[14:17], v[148:151], v[206:209], v[14:17]
	v_mfma_f32_16x16x32_bf16 v[10:13], v[156:159], v[206:209], v[10:13]
	v_mfma_f32_16x16x32_bf16 v[62:65], v[152:155], v[186:189], v[62:65]
	v_mfma_f32_16x16x32_bf16 v[58:61], v[160:163], v[186:189], v[58:61]
	v_mfma_f32_16x16x32_bf16 v[46:49], v[152:155], v[194:197], v[46:49]
	v_mfma_f32_16x16x32_bf16 v[42:45], v[160:163], v[194:197], v[42:45]
	v_mfma_f32_16x16x32_bf16 v[30:33], v[152:155], v[202:205], v[30:33]
	v_mfma_f32_16x16x32_bf16 v[26:29], v[160:163], v[202:205], v[26:29]
	v_mfma_f32_16x16x32_bf16 v[14:17], v[152:155], v[210:213], v[14:17]
	v_mfma_f32_16x16x32_bf16 v[10:13], v[160:163], v[210:213], v[10:13]
	v_mfma_f32_16x16x32_bf16 v[54:57], v[164:167], v[182:185], v[54:57]
	v_mfma_f32_16x16x32_bf16 v[50:53], v[172:175], v[182:185], v[50:53]
	v_mfma_f32_16x16x32_bf16 v[38:41], v[164:167], v[190:193], v[38:41]
	v_mfma_f32_16x16x32_bf16 v[34:37], v[172:175], v[190:193], v[34:37]
	v_mfma_f32_16x16x32_bf16 v[22:25], v[164:167], v[198:201], v[22:25]
	v_mfma_f32_16x16x32_bf16 v[18:21], v[172:175], v[198:201], v[18:21]
	v_mfma_f32_16x16x32_bf16 v[6:9], v[164:167], v[206:209], v[6:9]
	v_mfma_f32_16x16x32_bf16 v[2:5], v[172:175], v[206:209], v[2:5]
	v_mfma_f32_16x16x32_bf16 v[54:57], v[168:171], v[186:189], v[54:57]
	v_mfma_f32_16x16x32_bf16 v[50:53], v[176:179], v[186:189], v[50:53]
	v_mfma_f32_16x16x32_bf16 v[38:41], v[168:171], v[194:197], v[38:41]
	v_mfma_f32_16x16x32_bf16 v[34:37], v[176:179], v[194:197], v[34:37]
	v_mfma_f32_16x16x32_bf16 v[22:25], v[168:171], v[202:205], v[22:25]
	v_mfma_f32_16x16x32_bf16 v[18:21], v[176:179], v[202:205], v[18:21]
	v_mfma_f32_16x16x32_bf16 v[6:9], v[168:171], v[210:213], v[6:9]
	v_mfma_f32_16x16x32_bf16 v[2:5], v[176:179], v[210:213], v[2:5]
	s_setprio 0
	s_barrier
	s_add_i32 s51, 0, 0x18000
	v_add_u32_e32 v142, s51, v143
	s_add_i32 s52, 0, 0x1c000
	ds_read_b128 v[148:151], v142
	ds_read_b128 v[152:155], v142 offset:1024
	ds_read_b128 v[156:159], v142 offset:2048
	ds_read_b128 v[160:163], v142 offset:3072
	v_add_u32_e32 v142, s52, v143
	ds_read_b128 v[164:167], v142
	ds_read_b128 v[168:171], v142 offset:1024
	ds_read_b128 v[172:175], v142 offset:2048
	ds_read_b128 v[176:179], v142 offset:3072
	s_add_u32 s24, s24, 0x40000
	s_addc_u32 s25, s25, 0
	s_mov_b32 m0, s36
	v_lshl_add_u64 v[232:233], s[24:25], 0, v[136:137]
	ds_read_b128 v[182:185], v147 offset:32768
	ds_read_b128 v[186:189], v147 offset:33792
	ds_read_b128 v[190:193], v147 offset:34816
	ds_read_b128 v[194:197], v147 offset:35840
	ds_read_b128 v[198:201], v147 offset:36864
	ds_read_b128 v[202:205], v147 offset:37888
	ds_read_b128 v[206:209], v147 offset:38912
	ds_read_b128 v[210:213], v147 offset:39936
	global_load_lds_dwordx4 v[232:233], off
	v_lshl_add_u64 v[232:233], s[24:25], 0, v[132:133]
	s_mov_b32 m0, s37
	s_nop 0
	global_load_lds_dwordx4 v[232:233], off
	s_waitcnt vmcnt(8)
	s_waitcnt lgkmcnt(0)
	s_barrier
	s_setprio 1
	v_mfma_f32_16x16x32_bf16 v[126:129], v[148:151], v[182:185], v[126:129]
	v_mfma_f32_16x16x32_bf16 v[122:125], v[156:159], v[182:185], v[122:125]
	v_mfma_f32_16x16x32_bf16 v[110:113], v[148:151], v[190:193], v[110:113]
	v_mfma_f32_16x16x32_bf16 v[106:109], v[156:159], v[190:193], v[106:109]
	v_mfma_f32_16x16x32_bf16 v[94:97], v[148:151], v[198:201], v[94:97]
	v_mfma_f32_16x16x32_bf16 v[90:93], v[156:159], v[198:201], v[90:93]
	v_mfma_f32_16x16x32_bf16 v[78:81], v[148:151], v[206:209], v[78:81]
	v_mfma_f32_16x16x32_bf16 v[74:77], v[156:159], v[206:209], v[74:77]
	v_mfma_f32_16x16x32_bf16 v[126:129], v[152:155], v[186:189], v[126:129]
	v_mfma_f32_16x16x32_bf16 v[122:125], v[160:163], v[186:189], v[122:125]
	v_mfma_f32_16x16x32_bf16 v[110:113], v[152:155], v[194:197], v[110:113]
	v_mfma_f32_16x16x32_bf16 v[106:109], v[160:163], v[194:197], v[106:109]
	v_mfma_f32_16x16x32_bf16 v[94:97], v[152:155], v[202:205], v[94:97]
	v_mfma_f32_16x16x32_bf16 v[90:93], v[160:163], v[202:205], v[90:93]
	v_mfma_f32_16x16x32_bf16 v[78:81], v[152:155], v[210:213], v[78:81]
	v_mfma_f32_16x16x32_bf16 v[74:77], v[160:163], v[210:213], v[74:77]
	v_mfma_f32_16x16x32_bf16 v[118:121], v[164:167], v[182:185], v[118:121]
	v_mfma_f32_16x16x32_bf16 v[114:117], v[172:175], v[182:185], v[114:117]
	v_mfma_f32_16x16x32_bf16 v[102:105], v[164:167], v[190:193], v[102:105]
	v_mfma_f32_16x16x32_bf16 v[98:101], v[172:175], v[190:193], v[98:101]
	v_mfma_f32_16x16x32_bf16 v[86:89], v[164:167], v[198:201], v[86:89]
	v_mfma_f32_16x16x32_bf16 v[82:85], v[172:175], v[198:201], v[82:85]
	v_mfma_f32_16x16x32_bf16 v[70:73], v[164:167], v[206:209], v[70:73]
	v_mfma_f32_16x16x32_bf16 v[66:69], v[172:175], v[206:209], v[66:69]
	v_mfma_f32_16x16x32_bf16 v[118:121], v[168:171], v[186:189], v[118:121]
	v_mfma_f32_16x16x32_bf16 v[114:117], v[176:179], v[186:189], v[114:117]
	v_mfma_f32_16x16x32_bf16 v[102:105], v[168:171], v[194:197], v[102:105]
	v_mfma_f32_16x16x32_bf16 v[98:101], v[176:179], v[194:197], v[98:101]
	v_mfma_f32_16x16x32_bf16 v[86:89], v[168:171], v[202:205], v[86:89]
	v_mfma_f32_16x16x32_bf16 v[82:85], v[176:179], v[202:205], v[82:85]
	v_mfma_f32_16x16x32_bf16 v[70:73], v[168:171], v[210:213], v[70:73]
	v_mfma_f32_16x16x32_bf16 v[66:69], v[176:179], v[210:213], v[66:69]
	s_setprio 0
	s_barrier
; #define PG8_STAGE(bufoff, gbase, voff) do { _Pragma("unroll") for (int _i = 0; _i < 2; ++_i) \
;         __builtin_amdgcn_global_load_lds((const unsigned*)((const char*)(gbase) + (voff)[_i]), (LAS unsigned*)(lds + (bufoff) + ldsw + _i * 8192), 16, 0, 0); } while (0)
; #define PG8_LDA(dst, b, h) do { _Pragma("unroll") for (int m = 0; m < 4; ++m) _Pragma("unroll") for (int k = 0; k < 2; ++k) dst[m][k] = *(const LAS bf16x8*)(lds + PG8_SA(b, h) + aoff + m * 2048 + k * 1024); } while (0)
; #define PG8_MMA(ai, bj, At, Bt) do { __builtin_amdgcn_s_setprio(1); _Pragma("unroll") for (int m = 0; m < 4; ++m) _Pragma("unroll") for (int n = 0; n < 2; ++n) _Pragma("unroll") for (int k = 0; k < 2; ++k) \
;         acc[ai][bj][m][n] = __builtin_amdgcn_mfma_f32_16x16x32_bf16(Bt[n][k], At[m][k], acc[ai][bj][m][n], 0, 0, 0); __builtin_amdgcn_s_setprio(0); } while (0)
; #define PG8_WAIT_V(n) asm volatile("s_waitcnt vmcnt(" #n ")" ::: "memory")
; #define PG8_WAIT_L(n) asm volatile("s_waitcnt lgkmcnt(" #n ")" ::: "memory")
; #define PG8_BAR __builtin_amdgcn_s_barrier()
; #define PG8_SCHED __builtin_amdgcn_sched_barrier(0)
; template <class Epi>
; __device__ __forceinline__ void gemm_phase(LAS unsigned char* lds, const Gemm g, const StaticOrder& S, const Epi& E) {
;     ...
;             PG8_LDA(At, 1, 1); PG8_STAGE(PG8_SB(1, 0), b3, voffB); PG8_STAGE(PG8_SB(1, 1), b3 + hB, voffB); PG8_STAGE(PG8_SA(1, 0), a3, voffA);
;             PG8_WAIT_V(8); PG8_WAIT_L(0); PG8_BAR; PG8_MMA(1, 0, At, B0); PG8_MMA(1, 1, At, B1); PG8_BAR; PG8_SCHED;
;         }
	s_add_i32 s24, s51, s31
	v_lshl_add_u64 v[214:215], v[214:215], 0, s[88:89]
	s_mov_b32 m0, s24
	ds_read_b128 v[182:185], v147 offset:49152
	ds_read_b128 v[186:189], v147 offset:50176
	ds_read_b128 v[190:193], v147 offset:51200
	ds_read_b128 v[194:197], v147 offset:52224
	ds_read_b128 v[198:201], v147 offset:53248
	ds_read_b128 v[202:205], v147 offset:54272
	ds_read_b128 v[206:209], v147 offset:55296
	ds_read_b128 v[210:213], v147 offset:56320
	global_load_lds_dwordx4 v[214:215], off
	s_add_i32 m0, s24, 0x2000
	s_add_u32 s22, s22, 0x40080
	v_lshl_add_u64 v[214:215], v[216:217], 0, s[88:89]
	s_addc_u32 s23, s23, 0
	s_add_i32 s24, s52, s31
	global_load_lds_dwordx4 v[214:215], off
	v_lshl_add_u64 v[214:215], s[22:23], 0, v[134:135]
	s_mov_b32 m0, s24
	s_nop 0
	global_load_lds_dwordx4 v[214:215], off
	v_lshl_add_u64 v[214:215], s[22:23], 0, v[130:131]
	s_add_i32 m0, s24, 0x2000
	s_nop 0
	global_load_lds_dwordx4 v[214:215], off
	v_lshl_add_u64 v[214:215], v[218:219], 0, s[88:89]
	s_mov_b32 m0, s38
	s_nop 0
	global_load_lds_dwordx4 v[214:215], off
	v_lshl_add_u64 v[214:215], v[220:221], 0, s[88:89]
	s_mov_b32 m0, s39
	s_nop 0
	global_load_lds_dwordx4 v[214:215], off
	s_waitcnt vmcnt(8)
	s_waitcnt lgkmcnt(0)
	s_barrier
	s_setprio 1
	v_mfma_f32_16x16x32_bf16 v[62:65], v[148:151], v[182:185], v[62:65]
	v_mfma_f32_16x16x32_bf16 v[58:61], v[156:159], v[182:185], v[58:61]
	v_mfma_f32_16x16x32_bf16 v[46:49], v[148:151], v[190:193], v[46:49]
	v_mfma_f32_16x16x32_bf16 v[42:45], v[156:159], v[190:193], v[42:45]
	v_mfma_f32_16x16x32_bf16 v[30:33], v[148:151], v[198:201], v[30:33]
	v_mfma_f32_16x16x32_bf16 v[26:29], v[156:159], v[198:201], v[26:29]
	v_mfma_f32_16x16x32_bf16 v[14:17], v[148:151], v[206:209], v[14:17]
	v_mfma_f32_16x16x32_bf16 v[10:13], v[156:159], v[206:209], v[10:13]
	v_mfma_f32_16x16x32_bf16 v[62:65], v[152:155], v[186:189], v[62:65]
	v_mfma_f32_16x16x32_bf16 v[58:61], v[160:163], v[186:189], v[58:61]
	v_mfma_f32_16x16x32_bf16 v[46:49], v[152:155], v[194:197], v[46:49]
	v_mfma_f32_16x16x32_bf16 v[42:45], v[160:163], v[194:197], v[42:45]
	v_mfma_f32_16x16x32_bf16 v[30:33], v[152:155], v[202:205], v[30:33]
	v_mfma_f32_16x16x32_bf16 v[26:29], v[160:163], v[202:205], v[26:29]
	v_mfma_f32_16x16x32_bf16 v[14:17], v[152:155], v[210:213], v[14:17]
	v_mfma_f32_16x16x32_bf16 v[10:13], v[160:163], v[210:213], v[10:13]
	v_mfma_f32_16x16x32_bf16 v[54:57], v[164:167], v[182:185], v[54:57]
	v_mfma_f32_16x16x32_bf16 v[50:53], v[172:175], v[182:185], v[50:53]
	v_mfma_f32_16x16x32_bf16 v[38:41], v[164:167], v[190:193], v[38:41]
	v_mfma_f32_16x16x32_bf16 v[34:37], v[172:175], v[190:193], v[34:37]
	v_mfma_f32_16x16x32_bf16 v[22:25], v[164:167], v[198:201], v[22:25]
	v_mfma_f32_16x16x32_bf16 v[18:21], v[172:175], v[198:201], v[18:21]
	v_mfma_f32_16x16x32_bf16 v[6:9], v[164:167], v[206:209], v[6:9]
	v_mfma_f32_16x16x32_bf16 v[2:5], v[172:175], v[206:209], v[2:5]
	v_mfma_f32_16x16x32_bf16 v[54:57], v[168:171], v[186:189], v[54:57]
	v_mfma_f32_16x16x32_bf16 v[50:53], v[176:179], v[186:189], v[50:53]
	v_mfma_f32_16x16x32_bf16 v[38:41], v[168:171], v[194:197], v[38:41]
	v_mfma_f32_16x16x32_bf16 v[34:37], v[176:179], v[194:197], v[34:37]
	v_mfma_f32_16x16x32_bf16 v[22:25], v[168:171], v[202:205], v[22:25]
	v_mfma_f32_16x16x32_bf16 v[18:21], v[176:179], v[202:205], v[18:21]
	v_mfma_f32_16x16x32_bf16 v[6:9], v[168:171], v[210:213], v[6:9]
	v_mfma_f32_16x16x32_bf16 v[2:5], v[176:179], v[210:213], v[2:5]
	s_setprio 0
	s_barrier
	s_add_i32 s50, s50, 2
	s_add_u32 s20, s20, 0x100
	s_addc_u32 s21, s21, 0
	s_add_u32 s48, s48, 0x100
	s_addc_u32 s49, s49, 0
	s_cmp_gt_u32 s50, 13
	s_cbranch_scc0 .LBB0_1550
	s_and_b64 vcc, exec, s[10:11]
	s_cbranch_vccz .LBB0_1553
	s_barrier

; #define PG8_STAGE(bufoff, gbase, voff) do { _Pragma("unroll") for (int _i = 0; _i < 2; ++_i) \
;         __builtin_amdgcn_global_load_lds((const unsigned*)((const char*)(gbase) + (voff)[_i]), (LAS unsigned*)(lds + (bufoff) + ldsw + _i * 8192), 16, 0, 0); } while (0)
; #define PG8_LDA(dst, b, h) do { _Pragma("unroll") for (int m = 0; m < 4; ++m) _Pragma("unroll") for (int k = 0; k < 2; ++k) dst[m][k] = *(const LAS bf16x8*)(lds + PG8_SA(b, h) + aoff + m * 2048 + k * 1024); } while (0)
; #define PG8_LDB(dst, b, h) do { _Pragma("unroll") for (int n = 0; n < 2; ++n) _Pragma("unroll") for (int k = 0; k < 2; ++k) dst[n][k] = *(const LAS bf16x8*)(lds + PG8_SB(b, h) + boff + n * 2048 + k * 1024); } while (0)
; #define PG8_MMA(ai, bj, At, Bt) do { __builtin_amdgcn_s_setprio(1); _Pragma("unroll") for (int m = 0; m < 4; ++m) _Pragma("unroll") for (int n = 0; n < 2; ++n) _Pragma("unroll") for (int k = 0; k < 2; ++k) \
;         acc[ai][bj][m][n] = __builtin_amdgcn_mfma_f32_16x16x32_bf16(Bt[n][k], At[m][k], acc[ai][bj][m][n], 0, 0, 0); __builtin_amdgcn_s_setprio(0); } while (0)
; #define PG8_WAIT_V(n) asm volatile("s_waitcnt vmcnt(" #n ")" ::: "memory")
; #define PG8_WAIT_L(n) asm volatile("s_waitcnt lgkmcnt(" #n ")" ::: "memory")
; #define PG8_BAR __builtin_amdgcn_s_barrier()
; #define PG8_SCHED __builtin_amdgcn_sched_barrier(0)
; template <class Epi>
; __device__ __forceinline__ void gemm_phase(LAS unsigned char* lds, const Gemm g, const StaticOrder& S, const Epi& E) {
;     ...
;         for (int t = 0; t < nt; t += 2) {
;             const bool last = (t == nt - 2);
;             const char* a1 = cA + (size_t)(t + 1) * kstep;
;             const char* a2 = last ? nA : cA + (size_t)(t + 2) * kstep; const char* b2 = last ? nB : cB + (size_t)(t + 2) * kstep;
;             const char* a3 = a2 + kstep; const char* b3 = b2 + kstep;
;             PG8_LDB(B0, 0, 0); PG8_LDB(B1, 0, 1); PG8_SCHED; PG8_LDA(At, 0, 0); PG8_STAGE(PG8_SA(1, 1), a1 + hA, voffA);
;             PG8_WAIT_V(8); PG8_WAIT_L(0); PG8_BAR; PG8_MMA(0, 0, At, B0); PG8_MMA(0, 1, At, B1); PG8_BAR; PG8_SCHED;
;             PG8_LDA(At, 0, 1); PG8_STAGE(PG8_SB(0, 0), b2, voffB); PG8_STAGE(PG8_SB(0, 1), b2 + hB, voffB); PG8_STAGE(PG8_SA(0, 0), a2, voffA);
;             PG8_WAIT_V(8); PG8_WAIT_L(0); PG8_BAR; PG8_MMA(1, 0, At, B0); PG8_MMA(1, 1, At, B1); PG8_BAR; PG8_SCHED;
.LBB0_1632:
	s_add_u32 s8, s10, 0x100
	s_addc_u32 s9, s11, 0
	s_add_i32 s70, 0, 0x10000
	s_cmp_eq_u32 s67, 40
	s_cselect_b32 s45, s39, s9
	s_cselect_b32 s44, s38, s8
	s_cselect_b32 s43, s41, s37
	s_cselect_b32 s42, s40, s35
	s_add_i32 s71, 0, 0x14000
	s_waitcnt lgkmcnt(0)
	v_add_u32_e32 v158, s70, v180
	v_add_u32_e32 v174, s71, v180
	ds_read_b128 v[146:149], v158
	ds_read_b128 v[150:153], v158 offset:1024
	ds_read_b128 v[154:157], v158 offset:2048
	ds_read_b128 v[158:161], v158 offset:3072
	ds_read_b128 v[162:165], v174
	ds_read_b128 v[166:169], v174 offset:1024
	ds_read_b128 v[170:173], v174 offset:2048
	ds_read_b128 v[174:177], v174 offset:3072
	v_lshl_add_u64 v[178:179], s[10:11], 0, v[142:143]
	s_add_i32 m0, s52, 0xc000
	ds_read_b128 v[182:185], v192
	ds_read_b128 v[196:199], v192 offset:1024
	ds_read_b128 v[200:203], v192 offset:2048
	ds_read_b128 v[204:207], v192 offset:3072
	ds_read_b128 v[208:211], v192 offset:4096
	ds_read_b128 v[212:215], v192 offset:5120
	ds_read_b128 v[216:219], v192 offset:6144
	ds_read_b128 v[232:235], v192 offset:7168
	global_load_lds_dwordx4 v[178:179], off
	v_lshl_add_u64 v[178:179], s[10:11], 0, v[144:145]
	s_add_i32 m0, s52, 0xe000
	s_nop 0
	global_load_lds_dwordx4 v[178:179], off
	s_waitcnt vmcnt(8)
	s_waitcnt lgkmcnt(0)
	s_barrier
	s_setprio 1
	v_mfma_f32_16x16x32_bf16 v[26:29], v[146:149], v[182:185], v[26:29]
	v_mfma_f32_16x16x32_bf16 v[30:33], v[154:157], v[182:185], v[30:33]
	v_mfma_f32_16x16x32_bf16 v[58:61], v[146:149], v[200:203], v[58:61]
	v_mfma_f32_16x16x32_bf16 v[62:65], v[154:157], v[200:203], v[62:65]
	v_mfma_f32_16x16x32_bf16 v[90:93], v[146:149], v[208:211], v[90:93]
	v_mfma_f32_16x16x32_bf16 v[94:97], v[154:157], v[208:211], v[94:97]
	v_mfma_f32_16x16x32_bf16 v[114:117], v[146:149], v[216:219], v[114:117]
	v_mfma_f32_16x16x32_bf16 v[118:121], v[154:157], v[216:219], v[118:121]
	v_mfma_f32_16x16x32_bf16 v[26:29], v[150:153], v[196:199], v[26:29]
	v_mfma_f32_16x16x32_bf16 v[30:33], v[158:161], v[196:199], v[30:33]
	v_mfma_f32_16x16x32_bf16 v[58:61], v[150:153], v[204:207], v[58:61]
	v_mfma_f32_16x16x32_bf16 v[62:65], v[158:161], v[204:207], v[62:65]
	v_mfma_f32_16x16x32_bf16 v[90:93], v[150:153], v[212:215], v[90:93]
	v_mfma_f32_16x16x32_bf16 v[94:97], v[158:161], v[212:215], v[94:97]
	v_mfma_f32_16x16x32_bf16 v[114:117], v[150:153], v[232:235], v[114:117]
	v_mfma_f32_16x16x32_bf16 v[118:121], v[158:161], v[232:235], v[118:121]
	v_mfma_f32_16x16x32_bf16 v[42:45], v[162:165], v[182:185], v[42:45]
	v_mfma_f32_16x16x32_bf16 v[46:49], v[170:173], v[182:185], v[46:49]
	v_mfma_f32_16x16x32_bf16 v[74:77], v[162:165], v[200:203], v[74:77]
	v_mfma_f32_16x16x32_bf16 v[78:81], v[170:173], v[200:203], v[78:81]
	v_mfma_f32_16x16x32_bf16 v[106:109], v[162:165], v[208:211], v[106:109]
	v_mfma_f32_16x16x32_bf16 v[110:113], v[170:173], v[208:211], v[110:113]
	v_mfma_f32_16x16x32_bf16 v[126:129], v[162:165], v[216:219], v[126:129]
	v_mfma_f32_16x16x32_bf16 v[122:125], v[170:173], v[216:219], v[122:125]
	v_mfma_f32_16x16x32_bf16 v[42:45], v[166:169], v[196:199], v[42:45]
	v_mfma_f32_16x16x32_bf16 v[46:49], v[174:177], v[196:199], v[46:49]
	v_mfma_f32_16x16x32_bf16 v[74:77], v[166:169], v[204:207], v[74:77]
	v_mfma_f32_16x16x32_bf16 v[78:81], v[174:177], v[204:207], v[78:81]
	v_mfma_f32_16x16x32_bf16 v[106:109], v[166:169], v[212:215], v[106:109]
	v_mfma_f32_16x16x32_bf16 v[110:113], v[174:177], v[212:215], v[110:113]
	v_mfma_f32_16x16x32_bf16 v[126:129], v[166:169], v[232:235], v[126:129]
	v_mfma_f32_16x16x32_bf16 v[122:125], v[174:177], v[232:235], v[122:125]
	s_setprio 0
	s_barrier
	s_add_i32 s10, s70, s47
	v_lshl_add_u64 v[178:179], s[42:43], 0, v[132:133]
	s_mov_b32 m0, s10
	ds_read_b128 v[182:185], v192 offset:16384
	ds_read_b128 v[196:199], v192 offset:17408
	ds_read_b128 v[200:203], v192 offset:18432
	ds_read_b128 v[204:207], v192 offset:19456
	ds_read_b128 v[208:211], v192 offset:20480
	ds_read_b128 v[212:215], v192 offset:21504
	ds_read_b128 v[216:219], v192 offset:22528
	ds_read_b128 v[232:235], v192 offset:23552
	global_load_lds_dwordx4 v[178:179], off
	s_add_i32 m0, s10, 0x2000
	s_add_u32 s10, s42, 0xb0000
	v_lshl_add_u64 v[186:187], s[42:43], 0, v[136:137]
	s_addc_u32 s11, s43, 0
	s_add_i32 s70, s71, s47
	global_load_lds_dwordx4 v[186:187], off
	v_lshl_add_u64 v[220:221], s[10:11], 0, v[132:133]
	s_mov_b32 m0, s70
	v_lshl_add_u64 v[236:237], s[44:45], 0, v[134:135]
	global_load_lds_dwordx4 v[220:221], off
	v_lshl_add_u64 v[220:221], s[10:11], 0, v[136:137]
	s_add_i32 m0, s70, 0x2000
	s_nop 0
	global_load_lds_dwordx4 v[220:221], off
	v_lshl_add_u64 v[220:221], s[44:45], 0, v[130:131]
	s_mov_b32 m0, s52
	s_nop 0
	global_load_lds_dwordx4 v[220:221], off
	s_mov_b32 m0, s53
	s_nop 0
	global_load_lds_dwordx4 v[236:237], off
	s_waitcnt vmcnt(8)
	s_waitcnt lgkmcnt(0)
	s_barrier
; #define PG8_STAGE(bufoff, gbase, voff) do { _Pragma("unroll") for (int _i = 0; _i < 2; ++_i) \
;         __builtin_amdgcn_global_load_lds((const unsigned*)((const char*)(gbase) + (voff)[_i]), (LAS unsigned*)(lds + (bufoff) + ldsw + _i * 8192), 16, 0, 0); } while (0)
; #define PG8_LDA(dst, b, h) do { _Pragma("unroll") for (int m = 0; m < 4; ++m) _Pragma("unroll") for (int k = 0; k < 2; ++k) dst[m][k] = *(const LAS bf16x8*)(lds + PG8_SA(b, h) + aoff + m * 2048 + k * 1024); } while (0)
; #define PG8_LDB(dst, b, h) do { _Pragma("unroll") for (int n = 0; n < 2; ++n) _Pragma("unroll") for (int k = 0; k < 2; ++k) dst[n][k] = *(const LAS bf16x8*)(lds + PG8_SB(b, h) + boff + n * 2048 + k * 1024); } while (0)
; #define PG8_MMA(ai, bj, At, Bt) do { __builtin_amdgcn_s_setprio(1); _Pragma("unroll") for (int m = 0; m < 4; ++m) _Pragma("unroll") for (int n = 0; n < 2; ++n) _Pragma("unroll") for (int k = 0; k < 2; ++k) \
;         acc[ai][bj][m][n] = __builtin_amdgcn_mfma_f32_16x16x32_bf16(Bt[n][k], At[m][k], acc[ai][bj][m][n], 0, 0, 0); __builtin_amdgcn_s_setprio(0); } while (0)
; #define PG8_WAIT_V(n) asm volatile("s_waitcnt vmcnt(" #n ")" ::: "memory")
; #define PG8_WAIT_L(n) asm volatile("s_waitcnt lgkmcnt(" #n ")" ::: "memory")
; #define PG8_BAR __builtin_amdgcn_s_barrier()
; #define PG8_SCHED __builtin_amdgcn_sched_barrier(0)
; template <class Epi>
; __device__ __forceinline__ void gemm_phase(LAS unsigned char* lds, const Gemm g, const StaticOrder& S, const Epi& E) {
;     ...
;             PG8_WAIT_V(8); PG8_WAIT_L(0); PG8_BAR; PG8_MMA(1, 0, At, B0); PG8_MMA(1, 1, At, B1); PG8_BAR; PG8_SCHED;
;             PG8_LDB(B0, 1, 0); PG8_LDB(B1, 1, 1); PG8_SCHED; PG8_LDA(At, 1, 0); PG8_STAGE(PG8_SA(0, 1), a2 + hA, voffA);
;             PG8_WAIT_V(8); PG8_WAIT_L(0); PG8_BAR; PG8_MMA(0, 0, At, B0); PG8_MMA(0, 1, At, B1); PG8_BAR; PG8_SCHED;
	s_setprio 1
	v_mfma_f32_16x16x32_bf16 v[102:105], v[146:149], v[182:185], v[102:105]
	v_mfma_f32_16x16x32_bf16 v[98:101], v[154:157], v[182:185], v[98:101]
	v_mfma_f32_16x16x32_bf16 v[70:73], v[146:149], v[200:203], v[70:73]
	v_mfma_f32_16x16x32_bf16 v[66:69], v[154:157], v[200:203], v[66:69]
	v_mfma_f32_16x16x32_bf16 v[38:41], v[146:149], v[208:211], v[38:41]
	v_mfma_f32_16x16x32_bf16 v[34:37], v[154:157], v[208:211], v[34:37]
	v_mfma_f32_16x16x32_bf16 v[14:17], v[146:149], v[216:219], v[14:17]
	v_mfma_f32_16x16x32_bf16 v[10:13], v[154:157], v[216:219], v[10:13]
	v_mfma_f32_16x16x32_bf16 v[102:105], v[150:153], v[196:199], v[102:105]
	v_mfma_f32_16x16x32_bf16 v[98:101], v[158:161], v[196:199], v[98:101]
	v_mfma_f32_16x16x32_bf16 v[70:73], v[150:153], v[204:207], v[70:73]
	v_mfma_f32_16x16x32_bf16 v[66:69], v[158:161], v[204:207], v[66:69]
	v_mfma_f32_16x16x32_bf16 v[38:41], v[150:153], v[212:215], v[38:41]
	v_mfma_f32_16x16x32_bf16 v[34:37], v[158:161], v[212:215], v[34:37]
	v_mfma_f32_16x16x32_bf16 v[14:17], v[150:153], v[232:235], v[14:17]
	v_mfma_f32_16x16x32_bf16 v[10:13], v[158:161], v[232:235], v[10:13]
	v_mfma_f32_16x16x32_bf16 v[86:89], v[162:165], v[182:185], v[86:89]
	v_mfma_f32_16x16x32_bf16 v[82:85], v[170:173], v[182:185], v[82:85]
	v_mfma_f32_16x16x32_bf16 v[54:57], v[162:165], v[200:203], v[54:57]
	v_mfma_f32_16x16x32_bf16 v[50:53], v[170:173], v[200:203], v[50:53]
	v_mfma_f32_16x16x32_bf16 v[22:25], v[162:165], v[208:211], v[22:25]
	v_mfma_f32_16x16x32_bf16 v[18:21], v[170:173], v[208:211], v[18:21]
	v_mfma_f32_16x16x32_bf16 v[6:9], v[162:165], v[216:219], v[6:9]
	v_mfma_f32_16x16x32_bf16 v[2:5], v[170:173], v[216:219], v[2:5]
	v_mfma_f32_16x16x32_bf16 v[86:89], v[166:169], v[196:199], v[86:89]
	v_mfma_f32_16x16x32_bf16 v[82:85], v[174:177], v[196:199], v[82:85]
	v_mfma_f32_16x16x32_bf16 v[54:57], v[166:169], v[204:207], v[54:57]
	v_mfma_f32_16x16x32_bf16 v[50:53], v[174:177], v[204:207], v[50:53]
	v_mfma_f32_16x16x32_bf16 v[22:25], v[166:169], v[212:215], v[22:25]
	v_mfma_f32_16x16x32_bf16 v[18:21], v[174:177], v[212:215], v[18:21]
	v_mfma_f32_16x16x32_bf16 v[6:9], v[166:169], v[232:235], v[6:9]
	v_mfma_f32_16x16x32_bf16 v[2:5], v[174:177], v[232:235], v[2:5]
	s_setprio 0
	s_barrier
	s_add_i32 s70, 0, 0x18000
	s_add_i32 s71, 0, 0x1c000
	v_add_u32_e32 v158, s70, v180
	v_add_u32_e32 v174, s71, v180
	ds_read_b128 v[146:149], v158
	ds_read_b128 v[150:153], v158 offset:1024
	ds_read_b128 v[154:157], v158 offset:2048
	ds_read_b128 v[158:161], v158 offset:3072
	ds_read_b128 v[162:165], v174
	ds_read_b128 v[166:169], v174 offset:1024
	ds_read_b128 v[170:173], v174 offset:2048
	ds_read_b128 v[174:177], v174 offset:3072
	s_add_u32 s10, s44, 0xb0000
	s_addc_u32 s11, s45, 0
	s_mov_b32 m0, s54
	v_lshl_add_u64 v[238:239], s[10:11], 0, v[130:131]
	ds_read_b128 v[182:185], v192 offset:32768
	ds_read_b128 v[196:199], v192 offset:33792
	ds_read_b128 v[200:203], v192 offset:34816
	ds_read_b128 v[204:207], v192 offset:35840
	ds_read_b128 v[208:211], v192 offset:36864
	ds_read_b128 v[212:215], v192 offset:37888
	ds_read_b128 v[216:219], v192 offset:38912
	ds_read_b128 v[232:235], v192 offset:39936
	global_load_lds_dwordx4 v[238:239], off
	v_lshl_add_u64 v[238:239], s[10:11], 0, v[134:135]
	s_mov_b32 m0, s55
	s_nop 0
	global_load_lds_dwordx4 v[238:239], off
	s_waitcnt vmcnt(8)
	s_waitcnt lgkmcnt(0)
	s_barrier
	s_setprio 1
	v_mfma_f32_16x16x32_bf16 v[26:29], v[146:149], v[182:185], v[26:29]
	v_mfma_f32_16x16x32_bf16 v[30:33], v[154:157], v[182:185], v[30:33]
	v_mfma_f32_16x16x32_bf16 v[58:61], v[146:149], v[200:203], v[58:61]
	v_mfma_f32_16x16x32_bf16 v[62:65], v[154:157], v[200:203], v[62:65]
	v_mfma_f32_16x16x32_bf16 v[90:93], v[146:149], v[208:211], v[90:93]
	v_mfma_f32_16x16x32_bf16 v[94:97], v[154:157], v[208:211], v[94:97]
	v_mfma_f32_16x16x32_bf16 v[114:117], v[146:149], v[216:219], v[114:117]
	v_mfma_f32_16x16x32_bf16 v[118:121], v[154:157], v[216:219], v[118:121]
	v_mfma_f32_16x16x32_bf16 v[26:29], v[150:153], v[196:199], v[26:29]
	v_mfma_f32_16x16x32_bf16 v[30:33], v[158:161], v[196:199], v[30:33]
	v_mfma_f32_16x16x32_bf16 v[58:61], v[150:153], v[204:207], v[58:61]
	v_mfma_f32_16x16x32_bf16 v[62:65], v[158:161], v[204:207], v[62:65]
	v_mfma_f32_16x16x32_bf16 v[90:93], v[150:153], v[212:215], v[90:93]
	v_mfma_f32_16x16x32_bf16 v[94:97], v[158:161], v[212:215], v[94:97]
	v_mfma_f32_16x16x32_bf16 v[114:117], v[150:153], v[232:235], v[114:117]
	v_mfma_f32_16x16x32_bf16 v[118:121], v[158:161], v[232:235], v[118:121]
	v_mfma_f32_16x16x32_bf16 v[42:45], v[162:165], v[182:185], v[42:45]
	v_mfma_f32_16x16x32_bf16 v[46:49], v[170:173], v[182:185], v[46:49]
	v_mfma_f32_16x16x32_bf16 v[74:77], v[162:165], v[200:203], v[74:77]
	v_mfma_f32_16x16x32_bf16 v[78:81], v[170:173], v[200:203], v[78:81]
	v_mfma_f32_16x16x32_bf16 v[106:109], v[162:165], v[208:211], v[106:109]
	v_mfma_f32_16x16x32_bf16 v[110:113], v[170:173], v[208:211], v[110:113]
	v_mfma_f32_16x16x32_bf16 v[126:129], v[162:165], v[216:219], v[126:129]
	v_mfma_f32_16x16x32_bf16 v[122:125], v[170:173], v[216:219], v[122:125]
	v_mfma_f32_16x16x32_bf16 v[42:45], v[166:169], v[196:199], v[42:45]
	v_mfma_f32_16x16x32_bf16 v[46:49], v[174:177], v[196:199], v[46:49]
	v_mfma_f32_16x16x32_bf16 v[74:77], v[166:169], v[204:207], v[74:77]
	v_mfma_f32_16x16x32_bf16 v[78:81], v[174:177], v[204:207], v[78:81]
	v_mfma_f32_16x16x32_bf16 v[106:109], v[166:169], v[212:215], v[106:109]
	v_mfma_f32_16x16x32_bf16 v[110:113], v[174:177], v[212:215], v[110:113]
	v_mfma_f32_16x16x32_bf16 v[126:129], v[166:169], v[232:235], v[126:129]
	v_mfma_f32_16x16x32_bf16 v[122:125], v[174:177], v[232:235], v[122:125]
	s_setprio 0
	s_barrier
; #define PG8_STAGE(bufoff, gbase, voff) do { _Pragma("unroll") for (int _i = 0; _i < 2; ++_i) \
;         __builtin_amdgcn_global_load_lds((const unsigned*)((const char*)(gbase) + (voff)[_i]), (LAS unsigned*)(lds + (bufoff) + ldsw + _i * 8192), 16, 0, 0); } while (0)
; #define PG8_LDA(dst, b, h) do { _Pragma("unroll") for (int m = 0; m < 4; ++m) _Pragma("unroll") for (int k = 0; k < 2; ++k) dst[m][k] = *(const LAS bf16x8*)(lds + PG8_SA(b, h) + aoff + m * 2048 + k * 1024); } while (0)
; #define PG8_MMA(ai, bj, At, Bt) do { __builtin_amdgcn_s_setprio(1); _Pragma("unroll") for (int m = 0; m < 4; ++m) _Pragma("unroll") for (int n = 0; n < 2; ++n) _Pragma("unroll") for (int k = 0; k < 2; ++k) \
;         acc[ai][bj][m][n] = __builtin_amdgcn_mfma_f32_16x16x32_bf16(Bt[n][k], At[m][k], acc[ai][bj][m][n], 0, 0, 0); __builtin_amdgcn_s_setprio(0); } while (0)
; #define PG8_WAIT_V(n) asm volatile("s_waitcnt vmcnt(" #n ")" ::: "memory")
; #define PG8_WAIT_L(n) asm volatile("s_waitcnt lgkmcnt(" #n ")" ::: "memory")
; #define PG8_BAR __builtin_amdgcn_s_barrier()
; #define PG8_SCHED __builtin_amdgcn_sched_barrier(0)
; template <class Epi>
; __device__ __forceinline__ void gemm_phase(LAS unsigned char* lds, const Gemm g, const StaticOrder& S, const Epi& E) {
;     ...
;             PG8_LDA(At, 1, 1); PG8_STAGE(PG8_SB(1, 0), b3, voffB); PG8_STAGE(PG8_SB(1, 1), b3 + hB, voffB); PG8_STAGE(PG8_SA(1, 0), a3, voffA);
;             PG8_WAIT_V(8); PG8_WAIT_L(0); PG8_BAR; PG8_MMA(1, 0, At, B0); PG8_MMA(1, 1, At, B1); PG8_BAR; PG8_SCHED;
;         }
	s_add_i32 s10, s70, s47
	v_lshl_add_u64 v[178:179], v[178:179], 0, s[88:89]
	s_mov_b32 m0, s10
	ds_read_b128 v[182:185], v192 offset:49152
	ds_read_b128 v[196:199], v192 offset:50176
	ds_read_b128 v[200:203], v192 offset:51200
	ds_read_b128 v[204:207], v192 offset:52224
	ds_read_b128 v[208:211], v192 offset:53248
	ds_read_b128 v[212:215], v192 offset:54272
	ds_read_b128 v[216:219], v192 offset:55296
	ds_read_b128 v[232:235], v192 offset:56320
	global_load_lds_dwordx4 v[178:179], off
	s_add_i32 m0, s10, 0x2000
	s_add_u32 s10, s42, 0xb0080
	v_lshl_add_u64 v[178:179], v[186:187], 0, s[88:89]
	s_addc_u32 s11, s43, 0
	s_add_i32 s42, s71, s47
	global_load_lds_dwordx4 v[178:179], off
	v_lshl_add_u64 v[178:179], s[10:11], 0, v[132:133]
	s_mov_b32 m0, s42
	s_nop 0
	global_load_lds_dwordx4 v[178:179], off
	v_lshl_add_u64 v[178:179], s[10:11], 0, v[136:137]
	s_add_i32 m0, s42, 0x2000
	s_nop 0
	global_load_lds_dwordx4 v[178:179], off
	v_lshl_add_u64 v[178:179], v[220:221], 0, s[88:89]
	s_mov_b32 m0, s56
	s_nop 0
	global_load_lds_dwordx4 v[178:179], off
	v_lshl_add_u64 v[178:179], v[236:237], 0, s[88:89]
	s_mov_b32 m0, s57
	s_nop 0
	global_load_lds_dwordx4 v[178:179], off
	s_waitcnt vmcnt(8)
	s_waitcnt lgkmcnt(0)
	s_barrier
	s_setprio 1
	v_mfma_f32_16x16x32_bf16 v[102:105], v[146:149], v[182:185], v[102:105]
	v_mfma_f32_16x16x32_bf16 v[98:101], v[154:157], v[182:185], v[98:101]
	v_mfma_f32_16x16x32_bf16 v[70:73], v[146:149], v[200:203], v[70:73]
	v_mfma_f32_16x16x32_bf16 v[66:69], v[154:157], v[200:203], v[66:69]
	v_mfma_f32_16x16x32_bf16 v[38:41], v[146:149], v[208:211], v[38:41]
	v_mfma_f32_16x16x32_bf16 v[34:37], v[154:157], v[208:211], v[34:37]
	v_mfma_f32_16x16x32_bf16 v[14:17], v[146:149], v[216:219], v[14:17]
	v_mfma_f32_16x16x32_bf16 v[10:13], v[154:157], v[216:219], v[10:13]
	v_mfma_f32_16x16x32_bf16 v[102:105], v[150:153], v[196:199], v[102:105]
	v_mfma_f32_16x16x32_bf16 v[98:101], v[158:161], v[196:199], v[98:101]
	v_mfma_f32_16x16x32_bf16 v[70:73], v[150:153], v[204:207], v[70:73]
	v_mfma_f32_16x16x32_bf16 v[66:69], v[158:161], v[204:207], v[66:69]
	v_mfma_f32_16x16x32_bf16 v[38:41], v[150:153], v[212:215], v[38:41]
	v_mfma_f32_16x16x32_bf16 v[34:37], v[158:161], v[212:215], v[34:37]
	v_mfma_f32_16x16x32_bf16 v[14:17], v[150:153], v[232:235], v[14:17]
	v_mfma_f32_16x16x32_bf16 v[10:13], v[158:161], v[232:235], v[10:13]
	v_mfma_f32_16x16x32_bf16 v[86:89], v[162:165], v[182:185], v[86:89]
	v_mfma_f32_16x16x32_bf16 v[82:85], v[170:173], v[182:185], v[82:85]
	v_mfma_f32_16x16x32_bf16 v[54:57], v[162:165], v[200:203], v[54:57]
	v_mfma_f32_16x16x32_bf16 v[50:53], v[170:173], v[200:203], v[50:53]
	v_mfma_f32_16x16x32_bf16 v[22:25], v[162:165], v[208:211], v[22:25]
	v_mfma_f32_16x16x32_bf16 v[18:21], v[170:173], v[208:211], v[18:21]
	v_mfma_f32_16x16x32_bf16 v[6:9], v[162:165], v[216:219], v[6:9]
	v_mfma_f32_16x16x32_bf16 v[2:5], v[170:173], v[216:219], v[2:5]
	v_mfma_f32_16x16x32_bf16 v[86:89], v[166:169], v[196:199], v[86:89]
	v_mfma_f32_16x16x32_bf16 v[82:85], v[174:177], v[196:199], v[82:85]
	v_mfma_f32_16x16x32_bf16 v[54:57], v[166:169], v[204:207], v[54:57]
	v_mfma_f32_16x16x32_bf16 v[50:53], v[174:177], v[204:207], v[50:53]
	v_mfma_f32_16x16x32_bf16 v[22:25], v[166:169], v[212:215], v[22:25]
	v_mfma_f32_16x16x32_bf16 v[18:21], v[174:177], v[212:215], v[18:21]
	v_mfma_f32_16x16x32_bf16 v[6:9], v[166:169], v[232:235], v[6:9]
	v_mfma_f32_16x16x32_bf16 v[2:5], v[174:177], v[232:235], v[2:5]
	s_setprio 0
	s_barrier
	s_add_i32 s67, s67, 2
	s_add_u32 s35, s35, 0x100
	s_addc_u32 s37, s37, 0
	s_cmp_gt_u32 s67, 41
	s_mov_b64 s[10:11], s[8:9]
	s_cbranch_scc0 .LBB0_1632
	s_and_b64 vcc, exec, s[20:21]
	s_cbranch_vccz .LBB0_1635
	s_barrier
